# adds ds_read hoisting in M2 (in-flight cap 4) on top of the M3 hoisting
# speedup vs baseline: 1.0065x; 1.0004x over previous
.LBB0_1398:
	s_or_b64 exec, exec, s[8:9]
	s_add_u32 s0, s34, s46
	s_addc_u32 s1, s35, s47
	s_lshl_b64 s[8:9], s[44:45], 2
	s_add_u32 s42, s52, s8
	s_addc_u32 s43, s53, s9
	s_lshl_b32 s8, s59, 4
	v_or_b32_e32 v26, s8, v48
	s_waitcnt lgkmcnt(0)
	s_barrier
	v_mul_lo_u32 v36, v26, s90
	v_lshlrev_b32_e32 v47, 1, v49
	v_mad_u32_u24 v34, v48, s90, v34
	ds_read_b128 v[38:41], v34 offset:18432
	v_add3_u32 v49, s60, v36, v47
	ds_read_b128 v[30:33], v49
	ds_read_b128 v[42:45], v34 offset:18496
	ds_read_b128 v[50:53], v49 offset:64
	s_nop 0
	s_nop 0
	v_ashrrev_i32_e32 v27, 31, v26
	v_lshlrev_b64 v[26:27], 8, v[26:27]
	v_lshl_add_u64 v[26:27], s[42:43], 0, v[26:27]
	v_lshlrev_b32_e32 v196, 2, v37
	s_nop 0
	s_nop 0
	ds_read_b128 v[54:57], v34 offset:20992
	ds_read_b128 v[58:61], v34 offset:21056
	v_lshl_add_u64 v[74:75], v[26:27], 0, v[196:197]
	s_waitcnt lgkmcnt(4)
	ds_read_b128 v[62:65], v34 offset:23552
	v_mfma_f32_16x16x32_bf16 v[26:29], v[38:41], v[30:33], 0
	s_nop 0
	ds_read_b128 v[66:69], v34 offset:23616
	v_lshlrev_b32_e32 v196, 1, v37
	s_waitcnt lgkmcnt(4)
	ds_read_b128 v[80:83], v34 offset:26112
	v_mfma_f32_16x16x32_bf16 v[26:29], v[42:45], v[50:53], v[26:29]
	s_ashr_i32 s9, s8, 31
	s_lshl_b64 s[8:9], s[8:9], 1
	s_add_u32 s8, s0, s8
	s_addc_u32 s9, s1, s9
	s_movk_i32 s0, 0x2000
	s_nop 2
	global_store_dwordx4 v[74:75], v[26:29], off
	s_waitcnt lgkmcnt(4)
	s_nop 0
	v_mfma_f32_16x16x32_bf16 v[26:29], v[54:57], v[30:33], 0
	s_waitcnt lgkmcnt(3)
	v_mfma_f32_16x16x32_bf16 v[26:29], v[58:61], v[50:53], v[26:29]
	s_nop 7
	global_store_dwordx4 v[74:75], v[26:29], off offset:64
	s_waitcnt lgkmcnt(2)
	s_nop 0
	v_mfma_f32_16x16x32_bf16 v[26:29], v[62:65], v[30:33], 0
	s_waitcnt lgkmcnt(1)
	v_mfma_f32_16x16x32_bf16 v[26:29], v[66:69], v[50:53], v[26:29]
	s_nop 7
	global_store_dwordx4 v[74:75], v[26:29], off offset:128
	s_nop 0
	s_waitcnt lgkmcnt(0)
	v_mfma_f32_16x16x32_bf16 v[70:73], v[80:83], v[30:33], 0
	ds_read_b128 v[30:33], v34 offset:26176
	v_add3_u32 v34, s62, v36, v47
	s_waitcnt lgkmcnt(0)
	v_mfma_f32_16x16x32_bf16 v[50:53], v[30:33], v[50:53], v[70:73]
	ds_read_b128 v[70:73], v34 offset:64
	ds_read_b128 v[84:87], v34
	s_nop 3
	s_nop 0
	s_nop 2
	global_store_dwordx4 v[74:75], v[50:53], off offset:192
	s_nop 0
	s_waitcnt lgkmcnt(0)
	v_mfma_f32_16x16x32_bf16 v[36:39], v[84:87], v[38:41], 0
	v_lshl_add_u64 v[74:75], s[8:9], 0, v[196:197]
	v_lshlrev_b32_e32 v196, 8, v48
	v_lshl_add_u64 v[40:41], v[74:75], 0, v[196:197]
	v_mfma_f32_16x16x32_bf16 v[36:39], v[70:73], v[42:45], v[36:39]
	v_add_co_u32_e32 v42, vcc, s0, v40
	s_mov_b32 s8, s58
	s_nop 0
	v_addc_co_u32_e32 v43, vcc, 0, v41, vcc
	v_mfma_f32_16x16x32_bf16 v[26:29], v[84:87], v[80:83], 0
	s_nop 2
	v_cvt_pk_bf16_f32 v36, v36, v37
	v_cvt_pk_bf16_f32 v37, v38, v39
	global_store_dwordx2 v[40:41], v[36:37], off
	v_mfma_f32_16x16x32_bf16 v[36:39], v[84:87], v[54:57], 0
	v_mfma_f32_16x16x32_bf16 v[36:39], v[70:73], v[58:61], v[36:39]
	v_mfma_f32_16x16x32_bf16 v[26:29], v[70:73], v[30:33], v[26:29]
	s_nop 6
	v_cvt_pk_bf16_f32 v36, v36, v37
	v_cvt_pk_bf16_f32 v37, v38, v39
	global_store_dwordx2 v[42:43], v[36:37], off offset:-4096
	v_mfma_f32_16x16x32_bf16 v[36:39], v[84:87], v[62:65], 0
	v_cvt_pk_bf16_f32 v26, v26, v27
	v_cvt_pk_bf16_f32 v27, v28, v29
	v_add_co_u32_e32 v28, vcc, 0x3000, v40
	v_mfma_f32_16x16x32_bf16 v[36:39], v[70:73], v[66:69], v[36:39]
	s_nop 0
	v_addc_co_u32_e32 v29, vcc, 0, v41, vcc
	global_store_dwordx2 v[28:29], v[26:27], off
	s_andn2_b64 vcc, exec, s[40:41]
	s_nop 3
	v_cvt_pk_bf16_f32 v36, v36, v37
	v_cvt_pk_bf16_f32 v37, v38, v39
	global_store_dwordx2 v[42:43], v[36:37], off
	s_waitcnt lgkmcnt(0)
	s_barrier
	s_cbranch_vccz .LBB0_1453

.LBB0_1405:
	v_ashrrev_i32_e32 v34, 4, v27
	v_lshlrev_b32_e32 v29, 1, v26
	v_mul_lo_u32 v28, v34, s64
	v_and_b32_e32 v196, 0xf0, v29
	v_add3_u32 v28, 0, v28, v196
	ds_read_b128 v[28:31], v28 offset:18432
	v_lshl_add_u32 v32, v34, 2, 0
	s_nop 0
	v_add_u32_e32 v32, 0x20200, v32
	ds_read_b32 v32, v32
	v_cmp_lt_i32_e32 vcc, s84, v27
	v_add_u32_e32 v26, 0x1000, v26
	s_waitcnt lgkmcnt(1)
	v_lshlrev_b32_e32 v36, 16, v28
	v_and_b32_e32 v37, 0xffff0000, v28
	v_lshlrev_b32_e32 v28, 16, v29
	v_and_b32_e32 v29, 0xffff0000, v29
	s_waitcnt lgkmcnt(0)
	v_pk_mul_f32 v[38:39], v[32:33], v[28:29] op_sel_hi:[0,1]
	v_lshlrev_b32_e32 v28, 16, v30
	v_and_b32_e32 v29, 0xffff0000, v30
	v_pk_mul_f32 v[40:41], v[32:33], v[28:29] op_sel_hi:[0,1]
	v_lshlrev_b32_e32 v28, 16, v31
	v_and_b32_e32 v29, 0xffff0000, v31
	v_pk_mul_f32 v[36:37], v[32:33], v[36:37] op_sel_hi:[0,1]
	v_pk_mul_f32 v[32:33], v[32:33], v[28:29] op_sel_hi:[0,1]
	v_cvt_pk_bf16_f32 v31, v32, v33
	v_lshlrev_b32_e32 v32, 7, v34
	v_ashrrev_i32_e32 v33, 31, v32
	v_lshl_add_u64 v[32:33], v[32:33], 1, s[42:43]
	v_cvt_pk_bf16_f32 v28, v36, v37
	v_cvt_pk_bf16_f32 v29, v38, v39
	v_cvt_pk_bf16_f32 v30, v40, v41
	v_lshl_add_u64 v[32:33], v[32:33], 0, v[196:197]
	global_store_dwordx4 v[32:33], v[28:31], off
	s_or_b64 s[46:47], vcc, s[46:47]
	s_nop 0
	v_add_u32_e32 v28, 0x200, v27
	v_mov_b32_e32 v27, v28
	s_andn2_b64 exec, exec, s[46:47]
	s_cbranch_execnz .LBB0_1405
.LBB0_1406:
	s_or_b64 exec, exec, s[8:9]
	v_ashrrev_i32_e32 v42, 2, v47
	v_and_b32_e32 v27, 31, v47
	v_and_b32_e32 v26, -8, v42
	v_lshl_add_u32 v34, v27, 3, 0
	v_mul_u32_u24_e32 v28, 0x240, v27
	v_lshlrev_b32_e32 v29, 1, v26
	v_add_u32_e32 v32, 0x20100, v34
	v_add3_u32 v44, 0, v28, v29
	ds_read_b128 v[28:31], v44 offset:37152
	ds_read_b128 v[36:39], v44 offset:36864
	ds_read_b64 v[32:33], v32
	s_ashr_i32 s59, s48, 6
	s_lshl_b64 s[46:47], s[44:45], 1
	s_waitcnt lgkmcnt(2)
	v_lshlrev_b32_e32 v41, 16, v28
	s_waitcnt lgkmcnt(1)
	v_lshlrev_b32_e32 v40, 16, v36
	s_add_u32 s8, s26, s46
	s_waitcnt lgkmcnt(0)
	v_pk_mul_f32 v[40:41], v[32:33], v[40:41]
	s_addc_u32 s9, s27, s47
	v_lshlrev_b32_e32 v196, 2, v27
	s_add_i32 s60, 0, 0x16000
	v_cvt_pk_bf16_f32 v45, v40, v41
	v_and_b32_e32 v41, 0xffff0000, v28
	v_and_b32_e32 v40, 0xffff0000, v36
	v_add_u32_e32 v27, s60, v196
	v_mul_lo_u32 v48, v26, s90
	v_pk_mul_f32 v[40:41], v[32:33], v[40:41]
	v_add_u32_e32 v49, v27, v48
	v_cvt_pk_bf16_f32 v28, v40, v41
	ds_write2_b32 v49, v45, v28 offset1:40
	v_lshlrev_b32_e32 v41, 16, v29
	v_lshlrev_b32_e32 v40, 16, v37
	v_and_b32_e32 v29, 0xffff0000, v29
	v_and_b32_e32 v28, 0xffff0000, v37
	v_pk_mul_f32 v[40:41], v[32:33], v[40:41]
	v_pk_mul_f32 v[28:29], v[32:33], v[28:29]
	v_cvt_pk_bf16_f32 v36, v40, v41
	v_cvt_pk_bf16_f32 v28, v28, v29
	ds_write2_b32 v49, v36, v28 offset0:80 offset1:120
	v_lshlrev_b32_e32 v29, 16, v30
	v_lshlrev_b32_e32 v28, 16, v38
	v_pk_mul_f32 v[28:29], v[32:33], v[28:29]
	v_add_u32_e32 v43, 0x20400, v34
	v_cvt_pk_bf16_f32 v36, v28, v29
	v_and_b32_e32 v29, 0xffff0000, v30
	v_and_b32_e32 v28, 0xffff0000, v38
	v_pk_mul_f32 v[28:29], v[32:33], v[28:29]
	s_add_i32 s62, 0, 0x1b000
	v_cvt_pk_bf16_f32 v28, v28, v29
	ds_write2_b32 v49, v36, v28 offset0:160 offset1:200
	v_lshlrev_b32_e32 v29, 16, v31
	v_lshlrev_b32_e32 v28, 16, v39
	v_pk_mul_f32 v[28:29], v[32:33], v[28:29]
	s_ashr_i32 s48, s48, 7
	v_cvt_pk_bf16_f32 v28, v28, v29
	ds_write_b32 v49, v28 offset:960
	v_and_b32_e32 v29, 0xffff0000, v31
	v_and_b32_e32 v28, 0xffff0000, v39
	v_pk_mul_f32 v[28:29], v[32:33], v[28:29]
	s_lshl_b32 s0, s59, 1
	v_cvt_pk_bf16_f32 v29, v28, v29
	v_or_b32_e32 v28, 7, v42
	v_mul_lo_u32 v45, v28, s90
	v_add_u32_e32 v27, v27, v45
	ds_write_b32 v27, v29
	ds_read_b128 v[30:33], v44 offset:288
	ds_read_b128 v[36:39], v44
	ds_read_b64 v[40:41], v43
	v_add_u32_e32 v27, s62, v196
	v_add_u32_e32 v48, v27, v48
	s_waitcnt lgkmcnt(2)
	v_lshlrev_b32_e32 v43, 16, v30
	s_waitcnt lgkmcnt(1)
	v_lshlrev_b32_e32 v42, 16, v36
	s_waitcnt lgkmcnt(0)
	v_pk_mul_f32 v[42:43], v[40:41], v[42:43]
	v_add_u32_e32 v27, v27, v45
	v_cvt_pk_bf16_f32 v29, v42, v43
	v_and_b32_e32 v43, 0xffff0000, v30
	v_and_b32_e32 v42, 0xffff0000, v36
	v_pk_mul_f32 v[42:43], v[40:41], v[42:43]
	s_and_b32 s49, s0, 2
	v_cvt_pk_bf16_f32 v30, v42, v43
	ds_write2_b32 v48, v29, v30 offset1:40
	v_lshlrev_b32_e32 v43, 16, v31
	v_lshlrev_b32_e32 v42, 16, v37
	v_and_b32_e32 v31, 0xffff0000, v31
	v_and_b32_e32 v30, 0xffff0000, v37
	v_pk_mul_f32 v[42:43], v[40:41], v[42:43]
	v_pk_mul_f32 v[30:31], v[40:41], v[30:31]
	v_cvt_pk_bf16_f32 v29, v42, v43
	v_cvt_pk_bf16_f32 v30, v30, v31
	ds_write2_b32 v48, v29, v30 offset0:80 offset1:120
	v_lshlrev_b32_e32 v31, 16, v32
	v_lshlrev_b32_e32 v30, 16, v38
	v_pk_mul_f32 v[30:31], v[40:41], v[30:31]
	v_lshl_add_u64 v[42:43], s[8:9], 0, v[196:197]
	v_cvt_pk_bf16_f32 v29, v30, v31
	v_and_b32_e32 v31, 0xffff0000, v32
	v_and_b32_e32 v30, 0xffff0000, v38
	v_pk_mul_f32 v[30:31], v[40:41], v[30:31]
	s_lshl_b32 s8, s48, 4
	v_cvt_pk_bf16_f32 v30, v30, v31
	ds_write2_b32 v48, v29, v30 offset0:160 offset1:200
	v_lshlrev_b32_e32 v31, 16, v33
	v_lshlrev_b32_e32 v30, 16, v39
	v_pk_mul_f32 v[30:31], v[40:41], v[30:31]
	s_cmp_le_i32 s49, s48
	v_cvt_pk_bf16_f32 v29, v30, v31
	v_and_b32_e32 v31, 0xffff0000, v33
	v_and_b32_e32 v30, 0xffff0000, v39
	v_pk_mul_f32 v[30:31], v[40:41], v[30:31]
	ds_write_b32 v48, v29 offset:960
	v_cvt_pk_bf16_f32 v29, v30, v31
	ds_write_b32 v27, v29
	ds_read_b128 v[30:33], v44
	ds_read_b128 v[36:39], v44 offset:288
	v_add_u32_e32 v27, 0x20300, v34
	ds_read_b64 v[40:41], v27
	v_ashrrev_i32_e32 v27, 31, v26
	s_waitcnt lgkmcnt(2)
	v_lshlrev_b32_e32 v44, 16, v30
	s_waitcnt lgkmcnt(1)
	v_lshlrev_b32_e32 v45, 16, v36
	v_and_b32_e32 v48, 15, v47
	s_waitcnt lgkmcnt(0)
	v_pk_mul_f32 v[44:45], v[40:41], v[44:45]
	v_lshl_or_b32 v196, s49, 4, v48
	v_cvt_pk_bf16_f32 v29, v44, v45
	v_lshlrev_b64 v[44:45], 7, v[26:27]
	v_lshl_add_u64 v[44:45], v[42:43], 0, v[44:45]
	global_store_dword v[44:45], v29, off
	v_and_b32_e32 v45, 0xffff0000, v36
	v_and_b32_e32 v44, 0xffff0000, v30
	v_pk_mul_f32 v[44:45], v[40:41], v[44:45]
	v_and_b32_e32 v36, 0xffff0000, v31
	v_cvt_pk_bf16_f32 v27, v44, v45
	v_or_b32_e32 v44, 1, v26
	v_ashrrev_i32_e32 v45, 31, v44
	v_lshlrev_b64 v[44:45], 7, v[44:45]
	v_lshl_add_u64 v[44:45], v[42:43], 0, v[44:45]
	global_store_dword v[44:45], v27, off
	v_lshlrev_b32_e32 v45, 16, v37
	v_lshlrev_b32_e32 v44, 16, v31
	v_pk_mul_f32 v[44:45], v[40:41], v[44:45]
	v_and_b32_e32 v37, 0xffff0000, v37
	v_cvt_pk_bf16_f32 v27, v44, v45
	v_or_b32_e32 v44, 2, v26
	v_ashrrev_i32_e32 v45, 31, v44
	v_lshlrev_b64 v[44:45], 7, v[44:45]
	v_lshl_add_u64 v[44:45], v[42:43], 0, v[44:45]
	v_pk_mul_f32 v[30:31], v[40:41], v[36:37]
	global_store_dword v[44:45], v27, off
	v_cvt_pk_bf16_f32 v27, v30, v31
	v_or_b32_e32 v30, 3, v26
	v_ashrrev_i32_e32 v31, 31, v30
	v_lshlrev_b64 v[30:31], 7, v[30:31]
	v_lshl_add_u64 v[30:31], v[42:43], 0, v[30:31]
	global_store_dword v[30:31], v27, off
	v_lshlrev_b32_e32 v31, 16, v38
	v_lshlrev_b32_e32 v30, 16, v32
	v_pk_mul_f32 v[30:31], v[40:41], v[30:31]
	s_nop 0
	v_cvt_pk_bf16_f32 v27, v30, v31
	v_or_b32_e32 v30, 4, v26
	v_ashrrev_i32_e32 v31, 31, v30
	v_lshlrev_b64 v[30:31], 7, v[30:31]
	v_lshl_add_u64 v[30:31], v[42:43], 0, v[30:31]
	global_store_dword v[30:31], v27, off
	v_and_b32_e32 v31, 0xffff0000, v38
	v_and_b32_e32 v30, 0xffff0000, v32
	v_pk_mul_f32 v[30:31], v[40:41], v[30:31]
	v_mov_b32_e32 v38, 0
	v_cvt_pk_bf16_f32 v27, v30, v31
	v_or_b32_e32 v30, 5, v26
	v_ashrrev_i32_e32 v31, 31, v30
	v_lshlrev_b64 v[30:31], 7, v[30:31]
	v_lshl_add_u64 v[30:31], v[42:43], 0, v[30:31]
	v_or_b32_e32 v26, 6, v26
	global_store_dword v[30:31], v27, off
	v_lshlrev_b32_e32 v31, 16, v39
	v_lshlrev_b32_e32 v30, 16, v33
	v_ashrrev_i32_e32 v27, 31, v26
	v_pk_mul_f32 v[30:31], v[40:41], v[30:31]
	v_lshlrev_b64 v[26:27], 7, v[26:27]
	v_cvt_pk_bf16_f32 v29, v30, v31
	v_lshl_add_u64 v[26:27], v[42:43], 0, v[26:27]
	global_store_dword v[26:27], v29, off
	v_and_b32_e32 v27, 0xffff0000, v39
	v_and_b32_e32 v26, 0xffff0000, v33
	v_pk_mul_f32 v[26:27], v[40:41], v[26:27]
	v_ashrrev_i32_e32 v29, 31, v28
	v_cvt_pk_bf16_f32 v30, v26, v27
	v_lshlrev_b64 v[26:27], 7, v[28:29]
	v_lshl_add_u64 v[26:27], v[42:43], 0, v[26:27]
	global_store_dword v[26:27], v30, off
	v_lshrrev_b32_e32 v26, 1, v47
	v_and_b32_e32 v49, 24, v26
	v_lshl_add_u32 v34, v49, 1, 0
	v_or_b32_e32 v26, s8, v48
	s_waitcnt vmcnt(9)
	v_mad_u64_u32 v[36:37], s[42:43], v26, s64, v[34:35]
	v_mov_b32_e32 v30, 0
	v_mov_b32_e32 v31, 0
	v_mov_b32_e32 v32, 0
	v_mov_b32_e32 v33, 0
	v_mov_b32_e32 v26, 0
	v_mov_b32_e32 v27, 0
	v_mov_b32_e32 v28, 0
	v_mov_b32_e32 v29, 0
	s_cbranch_scc0 .LBB0_1408
	v_mad_u32_u24 v37, v196, s64, v34
	ds_read_b128 v[26:29], v37
	ds_read_b128 v[30:33], v36
	ds_read_b128 v[40:43], v36 offset:18432
	ds_read_b128 v[80:83], v37 offset:64
	ds_read_b128 v[52:55], v36 offset:64
	ds_read_b128 v[84:87], v36 offset:18496
	ds_read_b128 v[88:91], v37 offset:128
	s_waitcnt lgkmcnt(5)
	v_mfma_f32_16x16x32_bf16 v[30:33], v[30:33], v[26:29], 0
	s_waitcnt lgkmcnt(4)
	v_mfma_f32_16x16x32_bf16 v[26:29], v[40:43], v[26:29], 0
	s_nop 0
	s_nop 0
	s_waitcnt lgkmcnt(2)
	ds_read_b128 v[92:95], v36 offset:128
	ds_read_b128 v[96:99], v36 offset:18560
	v_mfma_f32_16x16x32_bf16 v[30:33], v[52:55], v[80:83], v[30:33]
	s_nop 0
	s_waitcnt lgkmcnt(3)
	ds_read_b128 v[100:103], v37 offset:192
	v_mfma_f32_16x16x32_bf16 v[26:29], v[84:87], v[80:83], v[26:29]
	s_nop 0
	s_nop 0
	s_waitcnt lgkmcnt(2)
	ds_read_b128 v[80:83], v36 offset:192
	ds_read_b128 v[84:87], v36 offset:18624
	v_mfma_f32_16x16x32_bf16 v[30:33], v[92:95], v[88:91], v[30:33]
	s_nop 0
	s_waitcnt lgkmcnt(3)
	v_mfma_f32_16x16x32_bf16 v[40:43], v[96:99], v[88:91], v[26:29]
	s_nop 0
	s_nop 1
	s_nop 0
	s_waitcnt lgkmcnt(1)
	v_mfma_f32_16x16x32_bf16 v[26:29], v[80:83], v[100:103], v[30:33]
	s_nop 2
	s_nop 0
	s_waitcnt lgkmcnt(0)
	v_mfma_f32_16x16x32_bf16 v[30:33], v[84:87], v[100:103], v[40:43]
.LBB0_1408:
	v_lshrrev_b32_e32 v37, 2, v47
	v_and_b32_e32 v37, 12, v37
	s_add_i32 s0, 0, 0x20000
	v_or_b32_e32 v39, s8, v37
	v_lshl_add_u32 v40, v196, 2, s0
	ds_read_b32 v44, v40
	v_lshl_add_u32 v43, v39, 2, s0
	ds_read_b32 v80, v43
	s_nop 0
	s_nop 0
	v_cmp_lt_i32_e32 vcc, v196, v39
	v_lshl_add_u32 v41, v39, 2, 0
	s_waitcnt lgkmcnt(0)
	v_sub_f32_e32 v40, v80, v44
	v_min_f32_e32 v40, 0, v40
	v_mul_f32_e32 v40, 0x3fb8aa3b, v40
	v_exp_f32_e32 v40, v40
	s_and_saveexec_b64 s[8:9], vcc
	s_cbranch_execz .LBB0_1410
	v_add_u32_e32 v38, 0x20100, v41
	ds_read_b32 v38, v38
	s_waitcnt lgkmcnt(0)
	v_mul_f32_e32 v38, v40, v38
	v_mul_f32_e32 v38, v26, v38

.LBB0_1412:
	s_or_b64 exec, exec, s[42:43]
	ds_write_b32 v45, v40 offset:55568
	v_lshlrev_b32_e32 v40, 6, v51
	v_mul_f32_e32 v27, v31, v30
	v_or_b32_e32 v30, v40, v196
	v_or_b32_e32 v54, 2, v39
	v_cvt_pk_bf16_f32 v27, v27, s0
	v_cmp_le_i32_e32 vcc, v196, v51
	v_ashrrev_i32_e32 v31, 31, v30
	v_lshl_add_u32 v55, v54, 2, 0
	v_cndmask_b32_e32 v27, 0, v27, vcc
	v_lshl_add_u64 v[30:31], v[30:31], 1, s[8:9]
	v_add_u32_e32 v56, 0x20000, v55
	ds_read_b32 v80, v56
	global_store_short v[30:31], v27, off
	s_nop 0
	v_cmp_lt_i32_e32 vcc, v196, v54
	s_waitcnt lgkmcnt(0)
	v_sub_f32_e32 v27, v80, v44
	v_min_f32_e32 v27, 0, v27
	v_mul_f32_e32 v27, 0x3fb8aa3b, v27
	v_exp_f32_e32 v27, v27
	s_and_saveexec_b64 s[42:43], vcc
	s_cbranch_execz .LBB0_1414
	v_add_u32_e32 v26, 0x20100, v55
	ds_read_b32 v26, v26
	s_waitcnt lgkmcnt(0)
	v_mul_f32_e32 v26, v27, v26
	v_mul_f32_e32 v26, v28, v26
.LBB0_1414:
	s_or_b64 exec, exec, s[42:43]
	ds_write_b32 v45, v26 offset:55840
	v_mul_f32_e32 v26, v32, v27
	v_cvt_pk_bf16_f32 v26, v26, s0
	v_cmp_le_i32_e32 vcc, v196, v54
	v_lshlrev_b32_e32 v42, 6, v54
	v_or_b32_e32 v57, 3, v39
	v_cndmask_b32_e32 v28, 0, v26, vcc
	v_or_b32_e32 v26, v42, v196
	v_ashrrev_i32_e32 v27, 31, v26
	v_lshl_add_u32 v58, v57, 2, 0
	v_lshl_add_u64 v[26:27], v[26:27], 1, s[8:9]
	v_add_u32_e32 v59, 0x20000, v58
	ds_read_b32 v80, v59
	global_store_short v[26:27], v28, off
	s_nop 0
	v_cmp_lt_i32_e32 vcc, v196, v57
	v_mov_b32_e32 v28, 0
	s_waitcnt lgkmcnt(0)
	v_sub_f32_e32 v27, v80, v44
	v_min_f32_e32 v27, 0, v27
	v_mul_f32_e32 v27, 0x3fb8aa3b, v27
	v_exp_f32_e32 v27, v27
	v_mov_b32_e32 v26, 0
	s_and_saveexec_b64 s[42:43], vcc
	s_cbranch_execz .LBB0_1416
	v_add_u32_e32 v28, 0x20100, v58
	ds_read_b32 v28, v28
	s_waitcnt lgkmcnt(0)
	v_mul_f32_e32 v28, v27, v28
	v_mul_f32_e32 v28, v29, v28
.LBB0_1416:
	s_or_b64 exec, exec, s[42:43]
	v_lshlrev_b32_e32 v44, 6, v57
	ds_write_b32 v45, v28 offset:56112
	v_mul_f32_e32 v27, v33, v27
	v_or_b32_e32 v28, v44, v196
	v_cvt_pk_bf16_f32 v27, v27, s0
	v_cmp_le_i32_e32 vcc, v196, v57
	v_ashrrev_i32_e32 v29, 31, v28
	v_lshl_add_u64 v[28:29], v[28:29], 1, s[8:9]
	v_cndmask_b32_e32 v27, 0, v27, vcc
	global_store_short v[28:29], v27, off
	s_cmp_ge_i32 s49, s48
	v_or_b32_e32 v60, 16, v196
	v_mov_b32_e32 v27, 0
	v_mov_b32_e32 v28, 0
	v_mov_b32_e32 v29, 0
	v_mov_b32_e32 v30, 0
	v_mov_b32_e32 v31, 0
	v_mov_b32_e32 v32, 0
	v_mov_b32_e32 v33, 0
	s_cbranch_scc1 .LBB0_1418
	v_mad_u32_u24 v61, v60, s64, v34
	ds_read_b128 v[26:29], v61
	ds_read_b128 v[30:33], v36
	ds_read_b128 v[62:65], v36 offset:18432
	ds_read_b128 v[80:83], v61 offset:64
	ds_read_b128 v[66:69], v36 offset:64
	ds_read_b128 v[84:87], v36 offset:18496
	ds_read_b128 v[88:91], v61 offset:128
	s_waitcnt lgkmcnt(5)
	v_mfma_f32_16x16x32_bf16 v[30:33], v[30:33], v[26:29], 0
	s_waitcnt lgkmcnt(4)
	v_mfma_f32_16x16x32_bf16 v[26:29], v[62:65], v[26:29], 0
	s_nop 0
	s_nop 0
	s_waitcnt lgkmcnt(2)
	ds_read_b128 v[92:95], v36 offset:128
	ds_read_b128 v[96:99], v36 offset:18560
	v_mfma_f32_16x16x32_bf16 v[30:33], v[66:69], v[80:83], v[30:33]
	s_nop 0
	s_waitcnt lgkmcnt(3)
	v_mfma_f32_16x16x32_bf16 v[26:29], v[84:87], v[80:83], v[26:29]
	s_nop 0
	s_nop 0
	s_waitcnt lgkmcnt(1)
	v_mfma_f32_16x16x32_bf16 v[30:33], v[92:95], v[88:91], v[30:33]
	s_nop 0
	s_waitcnt lgkmcnt(0)
	v_mfma_f32_16x16x32_bf16 v[26:29], v[96:99], v[88:91], v[26:29]
	ds_read_b128 v[62:65], v61 offset:192
	ds_read_b128 v[66:69], v36 offset:192
	s_waitcnt lgkmcnt(0)
	v_mfma_f32_16x16x32_bf16 v[30:33], v[66:69], v[62:65], v[30:33]
	ds_read_b128 v[66:69], v36 offset:18624
	s_waitcnt lgkmcnt(0)
	v_mfma_f32_16x16x32_bf16 v[26:29], v[66:69], v[62:65], v[26:29]

.LBB0_1424:
	s_or_b64 exec, exec, s[42:43]
	ds_write_b32 v45, v30 offset:55904
	ds_read_b32 v80, v59
	v_mul_f32_e32 v27, v28, v27
	s_nop 0
	v_cvt_pk_bf16_f32 v27, v27, s0
	v_cmp_le_i32_e32 vcc, v60, v54
	v_ashrrev_i32_e32 v43, 31, v42
	v_lshl_add_u64 v[30:31], v[196:197], 0, v[42:43]
	v_cndmask_b32_e32 v32, 0, v27, vcc
	s_waitcnt lgkmcnt(0)
	v_sub_f32_e32 v27, v80, v36
	v_min_f32_e32 v27, 0, v27
	v_mul_f32_e32 v27, 0x3fb8aa3b, v27
	v_exp_f32_e32 v27, v27
	v_lshl_add_u64 v[30:31], v[30:31], 1, s[8:9]
	v_cmp_lt_i32_e32 vcc, v60, v57
	global_store_short v[30:31], v32, off offset:32
	s_and_saveexec_b64 s[42:43], vcc
	s_cbranch_execz .LBB0_1426
	v_add_u32_e32 v26, 0x20100, v58
	ds_read_b32 v26, v26
	s_waitcnt lgkmcnt(0)
	v_mul_f32_e32 v26, v27, v26
	v_mul_f32_e32 v26, v33, v26
.LBB0_1426:
	s_or_b64 exec, exec, s[42:43]
	ds_write_b32 v45, v26 offset:56176
	v_mul_f32_e32 v26, v29, v27
	v_cvt_pk_bf16_f32 v26, v26, s0
	v_cmp_le_i32_e32 vcc, v60, v57
	v_ashrrev_i32_e32 v45, 31, v44
	s_cmp_lt_i32 s59, 4
	v_cndmask_b32_e32 v28, 0, v26, vcc
	v_lshl_add_u64 v[26:27], v[196:197], 0, v[44:45]
	v_lshl_add_u64 v[26:27], v[26:27], 1, s[8:9]
	global_store_short v[26:27], v28, off offset:32
	s_waitcnt lgkmcnt(0)
	s_barrier
	s_cselect_b64 s[8:9], -1, 0
	v_cmp_gt_u32_e32 vcc, 16, v50
	s_and_b64 s[42:43], s[8:9], vcc
	s_and_saveexec_b64 s[8:9], s[42:43]
	s_cbranch_execz .LBB0_1428
	s_lshl_b32 s0, s59, 6
	s_add_i32 s0, s0, 0
	s_mul_i32 s1, s59, 0x1100
	s_add_i32 s0, s0, s1
	v_mov_b32_e32 v44, s0
	ds_read_b32 v29, v44 offset:55568
	ds_read_b64 v[30:31], v44 offset:55840
	ds_read_b96 v[80:82], v44 offset:56112
	v_lshl_add_u32 v26, v50, 2, s0
	v_cmp_eq_u32_e32 vcc, 0, v50
	v_add_u32_e32 v42, 0x11c00, v26
	s_nop 0
	s_nop 0
	v_cndmask_b32_e64 v36, 0, 1.0, vcc
	v_cmp_eq_u32_e32 vcc, 1, v50
	v_add_u32_e32 v40, 0x800, v42
	v_add_u32_e32 v63, 0xc00, v42
	v_cndmask_b32_e64 v32, 0, 1.0, vcc
	v_cmp_eq_u32_e32 vcc, 2, v50
	s_waitcnt lgkmcnt(2)
	v_fma_f32 v45, -v36, v29, v32
	ds_write2_b32 v42, v36, v45 offset1:68
	ds_read_b128 v[84:87], v44 offset:56656
	ds_read_b128 v[88:91], v44 offset:56384
	v_cndmask_b32_e64 v29, 0, 1.0, vcc
	s_waitcnt lgkmcnt(4)
	v_fma_f32 v29, -v36, v30, v29
	v_cmp_eq_u32_e32 vcc, 3, v50
	v_fma_f32 v51, -v45, v31, v29
	s_nop 0
	v_cndmask_b32_e64 v29, 0, 1.0, vcc
	s_waitcnt lgkmcnt(3)
	v_fma_f32 v26, -v36, v80, v29
	v_fma_f32 v26, -v45, v81, v26
	v_fma_f32 v52, -v51, v82, v26
	s_nop 0
	v_cmp_eq_u32_e32 vcc, 4, v50
	ds_write2_b32 v42, v51, v52 offset0:136 offset1:204
	ds_read_b32 v80, v44 offset:56672
	ds_read_b128 v[92:95], v44 offset:56928
	s_nop 0
	v_cndmask_b32_e64 v38, 0, 1.0, vcc
	s_waitcnt lgkmcnt(3)
	ds_read_b64 v[96:97], v44 offset:56944
	v_fma_f32 v26, -v36, v88, v38
	v_fma_f32 v26, -v45, v89, v26
	v_fma_f32 v26, -v51, v90, v26
	v_cmp_eq_u32_e32 vcc, 5, v50
	v_fma_f32 v53, -v52, v91, v26
	s_nop 0
	v_cndmask_b32_e64 v26, 0, 1.0, vcc
	ds_read_b128 v[88:91], v44 offset:57200
	v_fma_f32 v26, -v36, v84, v26
	v_fma_f32 v26, -v45, v85, v26
	s_nop 0
	v_fma_f32 v26, -v51, v86, v26
	v_fma_f32 v31, -v52, v87, v26
	s_nop 0
	v_cmp_eq_u32_e32 vcc, 6, v50
	s_waitcnt lgkmcnt(3)
	v_fma_f32 v54, -v53, v80, v31
	v_add_u32_e32 v33, 0x400, v42
	v_cndmask_b32_e64 v30, 0, 1.0, vcc
	s_waitcnt lgkmcnt(2)
	v_fma_f32 v26, -v36, v92, v30
	s_nop 0
	v_fma_f32 v26, -v45, v93, v26
	v_fma_f32 v26, -v51, v94, v26
	v_fma_f32 v32, -v52, v95, v26
	s_nop 0
	s_waitcnt lgkmcnt(1)
	v_fma_f32 v30, -v53, v96, v32
	v_cmp_eq_u32_e32 vcc, 7, v50
	v_fma_f32 v55, -v54, v97, v30
	ds_write2_b32 v33, v53, v54 offset0:16 offset1:84
	ds_read_b96 v[80:82], v44 offset:57216
	ds_read_b128 v[84:87], v44 offset:57472
	v_cndmask_b32_e64 v30, 0, 1.0, vcc
	s_waitcnt lgkmcnt(3)
	v_fma_f32 v26, -v36, v88, v30
	s_nop 0
	v_fma_f32 v26, -v45, v89, v26
	v_fma_f32 v26, -v51, v90, v26
	v_fma_f32 v38, -v52, v91, v26
	s_nop 0
	s_waitcnt lgkmcnt(1)
	v_fma_f32 v30, -v53, v80, v38
	v_fma_f32 v30, -v54, v81, v30
	v_fma_f32 v56, -v55, v82, v30
	v_cmp_eq_u32_e32 vcc, 8, v50
	ds_write2_b32 v33, v55, v56 offset0:152 offset1:220
	ds_read_b128 v[30:33], v44 offset:57488
	ds_read_b128 v[80:83], v44 offset:57744
	ds_read_b128 v[88:91], v44 offset:57760
	ds_read_b32 v92, v44 offset:57776
	v_cndmask_b32_e64 v38, 0, 1.0, vcc
	s_waitcnt lgkmcnt(5)
	ds_read_b128 v[96:99], v44 offset:58016
	v_fma_f32 v26, -v36, v84, v38
	v_fma_f32 v26, -v45, v85, v26
	v_fma_f32 v26, -v51, v86, v26
	v_fma_f32 v38, -v52, v87, v26
	s_nop 0
	s_waitcnt lgkmcnt(4)
	v_fma_f32 v30, -v53, v30, v38
	v_fma_f32 v30, -v54, v31, v30
	v_fma_f32 v30, -v55, v32, v30
	v_cmp_eq_u32_e32 vcc, 9, v50
	v_fma_f32 v57, -v56, v33, v30
	s_nop 0
	v_cndmask_b32_e64 v30, 0, 1.0, vcc
	s_waitcnt lgkmcnt(3)
	ds_read_b128 v[84:87], v44 offset:58032
	v_fma_f32 v26, -v36, v80, v30
	s_nop 0
	v_fma_f32 v26, -v45, v81, v26
	v_fma_f32 v26, -v51, v82, v26
	v_fma_f32 v26, -v52, v83, v26
	s_nop 0
	s_waitcnt lgkmcnt(3)
	v_fma_f32 v26, -v53, v88, v26
	v_fma_f32 v26, -v54, v89, v26
	v_fma_f32 v26, -v55, v90, v26
	v_fma_f32 v26, -v56, v91, v26
	s_waitcnt lgkmcnt(2)
	v_fma_f32 v58, -v57, v92, v26
	s_nop 0
	s_nop 0
	v_cmp_eq_u32_e32 vcc, 10, v50
	ds_write2_b32 v40, v57, v58 offset0:32 offset1:100
	ds_read_b64 v[80:81], v44 offset:58048
	ds_read_b128 v[88:91], v44 offset:58288
	s_nop 0
	v_cndmask_b32_e64 v38, 0, 1.0, vcc
	s_waitcnt lgkmcnt(4)
	ds_read_b128 v[92:95], v44 offset:58304
	v_fma_f32 v26, -v36, v96, v38
	v_fma_f32 v26, -v45, v97, v26
	v_fma_f32 v26, -v51, v98, v26
	v_fma_f32 v26, -v52, v99, v26
	s_waitcnt lgkmcnt(4)
	ds_read_b96 v[96:98], v44 offset:58320
	v_fma_f32 v26, -v53, v84, v26
	s_nop 0
	v_fma_f32 v26, -v54, v85, v26
	v_fma_f32 v26, -v55, v86, v26
	v_fma_f32 v30, -v56, v87, v26
	s_nop 0
	s_waitcnt lgkmcnt(3)
	ds_read_b128 v[84:87], v44 offset:58560
	v_fma_f32 v30, -v57, v80, v30
	v_cmp_eq_u32_e32 vcc, 11, v50
	v_fma_f32 v59, -v58, v81, v30
	s_nop 0
	v_cndmask_b32_e64 v30, 0, 1.0, vcc
	s_waitcnt lgkmcnt(3)
	ds_read_b128 v[80:83], v44 offset:58576
	v_fma_f32 v26, -v36, v88, v30
	s_nop 0
	v_fma_f32 v26, -v45, v89, v26
	v_fma_f32 v26, -v51, v90, v26
	v_fma_f32 v29, -v52, v91, v26
	s_nop 0
	s_waitcnt lgkmcnt(3)
	v_fma_f32 v29, -v53, v92, v29
	v_fma_f32 v29, -v54, v93, v29
	v_fma_f32 v29, -v55, v94, v29
	v_fma_f32 v29, -v56, v95, v29
	s_waitcnt lgkmcnt(2)
	v_fma_f32 v26, -v57, v96, v29
	v_fma_f32 v26, -v58, v97, v26
	v_fma_f32 v60, -v59, v98, v26
	s_nop 0
	s_nop 0
	v_cmp_eq_u32_e32 vcc, 12, v50
	ds_write2_b32 v40, v59, v60 offset0:168 offset1:236
	ds_read_b128 v[88:91], v44 offset:58592
	ds_read_b128 v[92:95], v44 offset:58832
	s_nop 0
	v_cndmask_b32_e64 v38, 0, 1.0, vcc
	s_waitcnt lgkmcnt(4)
	ds_read_b128 v[96:99], v44 offset:58848
	v_fma_f32 v26, -v36, v84, v38
	v_fma_f32 v26, -v45, v85, v26
	v_fma_f32 v26, -v51, v86, v26
	v_fma_f32 v26, -v52, v87, v26
	s_waitcnt lgkmcnt(4)
	ds_read_b128 v[84:87], v44 offset:58864
	v_fma_f32 v30, -v53, v80, v26
	s_nop 0
	v_fma_f32 v30, -v54, v81, v30
	v_fma_f32 v30, -v55, v82, v30
	v_fma_f32 v38, -v56, v83, v30
	s_nop 0
	s_waitcnt lgkmcnt(3)
	ds_read_b32 v62, v44 offset:58880
	v_fma_f32 v26, -v57, v88, v38
	v_cmp_eq_u32_e32 vcc, 13, v50
	v_fma_f32 v26, -v58, v89, v26
	v_fma_f32 v26, -v59, v90, v26
	v_cndmask_b32_e64 v43, 0, 1.0, vcc
	s_waitcnt lgkmcnt(3)
	ds_read_b128 v[80:83], v44 offset:59104
	v_fma_f32 v30, -v36, v92, v43
	v_fma_f32 v61, -v60, v91, v26
	s_nop 0
	s_nop 0
	s_nop 0
	v_fma_f32 v30, -v45, v93, v30
	v_fma_f32 v30, -v51, v94, v30
	v_fma_f32 v30, -v52, v95, v30
	s_waitcnt lgkmcnt(3)
	v_fma_f32 v26, -v53, v96, v30
	v_fma_f32 v26, -v54, v97, v26
	v_fma_f32 v26, -v55, v98, v26
	v_fma_f32 v26, -v56, v99, v26
	s_waitcnt lgkmcnt(2)
	v_fma_f32 v26, -v57, v84, v26
	v_fma_f32 v26, -v58, v85, v26
	v_fma_f32 v26, -v59, v86, v26
	v_fma_f32 v30, -v60, v87, v26
	s_nop 0
	v_cmp_eq_u32_e32 vcc, 14, v50
	s_waitcnt lgkmcnt(1)
	v_fma_f32 v62, -v61, v62, v30
	ds_write2_b32 v63, v61, v62 offset0:48 offset1:116
	ds_read_b128 v[30:33], v44 offset:59120
	ds_read_b128 v[38:41], v44 offset:59136
	ds_read_b64 v[42:43], v44 offset:59152
	v_cndmask_b32_e64 v64, 0, 1.0, vcc
	s_waitcnt lgkmcnt(4)
	ds_read_b128 v[84:87], v44 offset:59376
	v_fma_f32 v26, -v36, v80, v64
	s_nop 0
	s_nop 0
	s_nop 0
	v_fma_f32 v26, -v45, v81, v26
	v_fma_f32 v26, -v51, v82, v26
	v_fma_f32 v26, -v52, v83, v26
	s_waitcnt lgkmcnt(3)
	ds_read_b128 v[80:83], v44 offset:59392
	v_fma_f32 v26, -v53, v30, v26
	v_fma_f32 v26, -v54, v31, v26
	v_fma_f32 v26, -v55, v32, v26
	v_fma_f32 v26, -v56, v33, v26
	s_waitcnt lgkmcnt(3)
	ds_read_b128 v[88:91], v44 offset:59408
	v_fma_f32 v26, -v57, v38, v26
	v_fma_f32 v26, -v58, v39, v26
	v_fma_f32 v26, -v59, v40, v26
	v_fma_f32 v30, -v60, v41, v26
	s_nop 0
	v_cmp_eq_u32_e32 vcc, 15, v50
	s_waitcnt lgkmcnt(3)
	ds_read_b96 v[92:94], v44 offset:59424
	v_fma_f32 v30, -v61, v42, v30
	v_fma_f32 v64, -v62, v43, v30
	v_cndmask_b32_e64 v50, 0, 1.0, vcc
	s_waitcnt lgkmcnt(3)
	v_fma_f32 v26, -v36, v84, v50
	s_nop 0
	s_nop 0
	s_nop 0
	v_fma_f32 v26, -v45, v85, v26
	v_fma_f32 v26, -v51, v86, v26
	v_fma_f32 v26, -v52, v87, v26
	s_waitcnt lgkmcnt(2)
	v_fma_f32 v26, -v53, v80, v26
	v_fma_f32 v26, -v54, v81, v26
	v_fma_f32 v26, -v55, v82, v26
	v_fma_f32 v26, -v56, v83, v26
	s_waitcnt lgkmcnt(1)
	v_fma_f32 v26, -v57, v88, v26
	v_fma_f32 v26, -v58, v89, v26
	v_fma_f32 v26, -v59, v90, v26
	v_fma_f32 v26, -v60, v91, v26
	s_waitcnt lgkmcnt(0)
	v_fma_f32 v26, -v61, v92, v26
	v_fma_f32 v26, -v62, v93, v26
	v_fma_f32 v26, -v64, v94, v26
	ds_write2_b32 v63, v64, v26 offset0:184 offset1:252

.LBB0_1430:
	v_ashrrev_i32_e32 v36, 8, v27
	v_bfe_u32 v56, v27, 4, 4
	v_lshlrev_b32_e32 v33, 4, v36
	v_or_b32_e32 v28, v33, v56
	v_lshlrev_b32_e32 v29, 6, v36
	v_mul_lo_u32 v28, v28, s36
	v_add_u32_e32 v32, v26, v29
	v_add3_u32 v50, v28, 0, v29
	ds_read_b128 v[28:31], v50 offset:59648
	ds_read_b128 v[38:41], v50 offset:59664
	ds_read_b128 v[42:45], v50 offset:59680
	ds_read_b128 v[80:83], v50 offset:59696
	v_mad_i32_i24 v57, v36, s37, v32
	s_nop 0
	s_nop 0
	s_nop 0
	s_nop 0
	ds_read_b32 v54, v57
	s_waitcnt lgkmcnt(0)
	v_fma_f32 v58, v28, v54, 0
	v_or_b32_e32 v28, 1, v33
	v_mad_u64_u32 v[32:33], s[42:43], v28, s36, v[32:33]
	ds_read2_b32 v[54:55], v32 offset1:68
	ds_read2_b32 v[84:85], v32 offset0:136 offset1:204
	v_cmp_lt_i32_e64 s[42:43], s25, v27
	s_or_b64 s[48:49], s[42:43], s[48:49]
	s_waitcnt lgkmcnt(1)
	v_fmac_f32_e32 v58, v29, v54
	s_nop 0
	v_fmac_f32_e32 v58, v30, v55
	s_waitcnt lgkmcnt(0)
	v_fmac_f32_e32 v58, v31, v84
	v_add_u32_e32 v28, 0x400, v57
	ds_read2_b32 v[30:31], v28 offset0:84 offset1:220
	v_mov_b32_e32 v28, v85
	s_waitcnt lgkmcnt(0)
	v_mov_b32_e32 v29, v30
	v_pk_mul_f32 v[28:29], v[38:39], v[28:29]
	s_nop 0
	v_add_f32_e32 v28, v58, v28
	v_add_f32_e32 v33, v28, v29
	v_add_u32_e32 v28, 0x400, v32
	ds_read2_b32 v[28:29], v28 offset0:84 offset1:220
	s_waitcnt lgkmcnt(0)
	v_mov_b32_e32 v30, v28
	v_pk_mul_f32 v[30:31], v[40:41], v[30:31]
	s_nop 0
	v_add_f32_e32 v28, v33, v30
	v_add_f32_e32 v33, v28, v31
	v_add_u32_e32 v28, 0x800, v57
	ds_read2_b32 v[30:31], v28 offset0:100 offset1:236
	v_mov_b32_e32 v28, v29
	s_waitcnt lgkmcnt(0)
	v_mov_b32_e32 v29, v30
	v_pk_mul_f32 v[28:29], v[42:43], v[28:29]
	s_nop 0
	v_add_f32_e32 v28, v33, v28
	v_add_f32_e32 v33, v28, v29
	v_add_u32_e32 v28, 0x800, v32
	ds_read2_b32 v[28:29], v28 offset0:100 offset1:236
	s_waitcnt lgkmcnt(0)
	v_mov_b32_e32 v30, v28
	v_pk_mul_f32 v[30:31], v[44:45], v[30:31]
	s_nop 0
	v_add_f32_e32 v28, v33, v30
	v_add_f32_e32 v33, v28, v31
	v_add_u32_e32 v28, 0xc00, v57
	ds_read2_b32 v[30:31], v28 offset0:116 offset1:252
	v_mov_b32_e32 v28, v29
	s_waitcnt lgkmcnt(0)
	v_mov_b32_e32 v29, v30
	ds_read_b32 v30, v32 offset:3536
	v_pk_mul_f32 v[28:29], v[80:81], v[28:29]
	s_nop 0
	v_add_f32_e32 v28, v33, v28
	v_add_f32_e32 v33, v28, v29
	s_waitcnt lgkmcnt(0)
	v_pk_mul_f32 v[28:29], v[82:83], v[30:31]
	v_mul_u32_u24_e32 v30, 0x44, v56
	v_add_f32_e32 v28, v33, v28
	v_add_f32_e32 v28, v28, v29
	v_mad_i32_i24 v29, v36, s18, 0
	v_lshlrev_b32_e32 v31, 2, v48
	v_add3_u32 v29, v29, v30, v31
	ds_write_b32 v29, v28 offset:36864
	v_add_u32_e32 v28, 0x200, v27
	v_mov_b32_e32 v27, v28
	s_andn2_b64 exec, exec, s[48:49]
	s_cbranch_execnz .LBB0_1430

.LBB0_1433:
	v_ashrrev_i32_e32 v28, 8, v27
	v_bfe_u32 v29, v27, 4, 4
	v_lshl_or_b32 v29, v28, 4, v29
	v_mul_lo_u32 v29, v29, s36
	s_add_i32 s0, 0, 0x11c00
	v_lshlrev_b32_e32 v30, 6, v28
	v_mad_i32_i24 v32, v28, s18, v26
	v_add3_u32 v36, v29, s0, v30
	ds_read_b128 v[28:31], v36 offset:4416
	ds_read_b128 v[38:41], v36 offset:4432
	ds_read_b128 v[42:45], v36 offset:4448
	ds_read_b128 v[50:53], v36 offset:4464
	v_add_u32_e32 v54, 0x9000, v32
	s_nop 0
	s_nop 0
	s_nop 0
	s_nop 0
	ds_read2_b32 v[32:33], v54 offset1:17
	v_cmp_lt_i32_e32 vcc, s25, v27
	s_or_b64 s[42:43], vcc, s[42:43]
	s_waitcnt lgkmcnt(0)
	ds_read2_b32 v[80:81], v54 offset0:34 offset1:51
	v_fma_f32 v32, v28, v32, 0
	v_fmac_f32_e32 v32, v29, v33
	s_nop 0
	s_waitcnt lgkmcnt(0)
	ds_read2_b32 v[84:85], v54 offset0:68 offset1:85
	v_fmac_f32_e32 v32, v30, v80
	v_fmac_f32_e32 v32, v31, v81
	s_nop 0
	s_waitcnt lgkmcnt(0)
	ds_read2_b32 v[80:81], v54 offset0:102 offset1:119
	ds_read2_b32 v[88:89], v54 offset0:136 offset1:153
	v_pk_mul_f32 v[28:29], v[38:39], v[84:85]
	s_nop 0
	v_add_f32_e32 v28, v32, v28
	v_add_f32_e32 v30, v28, v29
	s_nop 0
	s_waitcnt lgkmcnt(1)
	ds_read2_b32 v[84:85], v54 offset0:170 offset1:187
	v_pk_mul_f32 v[28:29], v[40:41], v[80:81]
	s_nop 0
	v_add_f32_e32 v28, v30, v28
	v_add_f32_e32 v30, v28, v29
	s_nop 0
	s_waitcnt lgkmcnt(1)
	ds_read2_b32 v[80:81], v54 offset0:204 offset1:221
	ds_read2_b32 v[92:93], v54 offset0:238 offset1:255
	v_pk_mul_f32 v[28:29], v[42:43], v[88:89]
	s_nop 0
	v_add_f32_e32 v28, v30, v28
	v_add_f32_e32 v30, v28, v29
	s_nop 0
	s_waitcnt lgkmcnt(2)
	v_pk_mul_f32 v[28:29], v[44:45], v[84:85]
	s_nop 0
	v_add_f32_e32 v28, v30, v28
	v_add_f32_e32 v30, v28, v29
	s_nop 0
	s_waitcnt lgkmcnt(1)
	v_pk_mul_f32 v[28:29], v[50:51], v[80:81]
	s_nop 0
	v_add_f32_e32 v28, v30, v28
	v_add_f32_e32 v30, v28, v29
	s_nop 0
	s_waitcnt lgkmcnt(0)
	v_pk_mul_f32 v[28:29], v[52:53], v[92:93]
	s_nop 0
	v_add_f32_e32 v28, v30, v28
	v_add_f32_e32 v28, v28, v29
	v_xor_b32_e32 v28, 0x80000000, v28
	v_lshl_add_u32 v29, v48, 2, v36
	ds_write_b32 v29, v28 offset:4352
	v_add_u32_e32 v28, 0x200, v27
	v_mov_b32_e32 v27, v28
	s_andn2_b64 exec, exec, s[42:43]
	s_cbranch_execnz .LBB0_1433

.LBB0_1436:
	v_ashrrev_i32_e32 v29, 8, v28
	v_bfe_u32 v58, v28, 4, 4
	v_lshlrev_b32_e32 v54, 4, v29
	v_or_b32_e32 v30, v54, v58
	v_lshlrev_b32_e32 v31, 6, v29
	v_mul_lo_u32 v30, v30, s36
	v_add_u32_e32 v36, v27, v31
	v_add3_u32 v59, v30, 0, v31
	ds_read_b128 v[30:33], v59 offset:64000
	ds_read_b128 v[38:41], v59 offset:64016
	ds_read_b128 v[42:45], v59 offset:64032
	ds_read_b128 v[50:53], v59 offset:64048
	v_mad_i32_i24 v60, v29, s37, v36
	s_nop 0
	s_nop 0
	s_nop 0
	s_nop 0
	ds_read_b32 v55, v60
	v_mad_i32_i24 v29, v29, s18, 0
	v_cmp_lt_i32_e64 s[42:43], -1, v28
	s_or_b64 s[50:51], s[42:43], s[50:51]
	s_waitcnt lgkmcnt(0)
	v_fma_f32 v61, v30, v55, 0
	v_or_b32_e32 v30, 1, v54
	v_mad_u64_u32 v[54:55], s[8:9], v30, s36, v[36:37]
	ds_read2_b32 v[56:57], v54 offset1:68
	ds_read2_b32 v[80:81], v54 offset0:136 offset1:204
	s_waitcnt lgkmcnt(1)
	v_fmac_f32_e32 v61, v31, v56
	s_nop 0
	v_fmac_f32_e32 v61, v32, v57
	v_add_u32_e32 v32, 0x400, v54
	s_waitcnt lgkmcnt(0)
	ds_read2_b32 v[84:85], v32 offset0:16 offset1:84
	v_fmac_f32_e32 v61, v33, v80
	ds_read2_b32 v[88:89], v32 offset0:152 offset1:220
	v_fmac_f32_e32 v61, v38, v81
	s_nop 0
	s_waitcnt lgkmcnt(1)
	v_fmac_f32_e32 v61, v39, v84
	v_fmac_f32_e32 v61, v40, v85
	s_nop 0
	v_add_u32_e32 v32, 0x800, v54
	ds_read2_b32 v[80:81], v32 offset0:32 offset1:100
	s_waitcnt lgkmcnt(1)
	ds_read2_b32 v[84:85], v32 offset0:168 offset1:236
	v_fmac_f32_e32 v61, v41, v88
	v_fmac_f32_e32 v61, v42, v89
	s_nop 0
	s_waitcnt lgkmcnt(1)
	v_fmac_f32_e32 v61, v43, v80
	v_fmac_f32_e32 v61, v44, v81
	s_nop 0
	v_add_u32_e32 v32, 0xc00, v54
	ds_read2_b32 v[38:39], v32 offset0:184 offset1:252
	ds_read2_b32 v[80:81], v32 offset0:48 offset1:116
	ds_read_b128 v[88:91], v59 offset:64064
	s_waitcnt lgkmcnt(3)
	v_fmac_f32_e32 v61, v45, v84
	v_fmac_f32_e32 v61, v50, v85
	s_nop 0
	s_waitcnt lgkmcnt(1)
	v_fmac_f32_e32 v61, v51, v80
	v_fmac_f32_e32 v61, v52, v81
	s_nop 0
	v_fmac_f32_e32 v61, v53, v38
	s_waitcnt lgkmcnt(0)
	v_fmac_f32_e32 v61, v88, v39
	v_add_u32_e32 v30, 0x1000, v54
	ds_read2_b32 v[38:39], v30 offset0:64 offset1:132
	v_add_u32_e32 v30, 0x1200, v54
	ds_read2_b32 v[80:81], v30 offset0:72 offset1:140
	s_waitcnt lgkmcnt(1)
	v_fmac_f32_e32 v61, v89, v38
	v_fmac_f32_e32 v61, v90, v39
	s_nop 0
	v_add_u32_e32 v30, 0x1600, v60
	ds_read2_b32 v[40:41], v30 offset0:20 offset1:156
	ds_read_b128 v[84:87], v59 offset:64080
	s_waitcnt lgkmcnt(2)
	v_fmac_f32_e32 v61, v91, v80
	s_nop 0
	s_nop 0
	v_mov_b32_e32 v38, v81
	s_waitcnt lgkmcnt(1)
	v_mov_b32_e32 v39, v40
	s_waitcnt lgkmcnt(0)
	v_pk_mul_f32 v[30:31], v[84:85], v[38:39]
	s_nop 0
	v_add_f32_e32 v30, v61, v30
	v_add_f32_e32 v36, v30, v31
	v_add_u32_e32 v30, 0x1600, v54
	ds_read2_b32 v[38:39], v30 offset0:20 offset1:156
	s_waitcnt lgkmcnt(0)
	v_mov_b32_e32 v40, v38
	v_pk_mul_f32 v[30:31], v[86:87], v[40:41]
	v_mov_b32_e32 v38, v39
	v_add_f32_e32 v30, v36, v30
	v_add_f32_e32 v36, v30, v31
	v_add_u32_e32 v30, 0x1a00, v60
	ds_read2_b32 v[40:41], v30 offset0:36 offset1:172
	ds_read_b128 v[30:33], v59 offset:64096
	s_waitcnt lgkmcnt(1)
	v_mov_b32_e32 v39, v40
	s_waitcnt lgkmcnt(0)
	v_pk_mul_f32 v[30:31], v[30:31], v[38:39]
	s_nop 0
	v_add_f32_e32 v30, v36, v30
	v_add_f32_e32 v36, v30, v31
	v_add_u32_e32 v30, 0x1a00, v54
	ds_read2_b32 v[38:39], v30 offset0:36 offset1:172
	s_waitcnt lgkmcnt(0)
	v_mov_b32_e32 v40, v38
	v_pk_mul_f32 v[30:31], v[32:33], v[40:41]
	v_mov_b32_e32 v38, v39
	v_add_f32_e32 v30, v36, v30
	v_add_f32_e32 v36, v30, v31
	v_add_u32_e32 v30, 0x1e00, v60
	ds_read2_b32 v[40:41], v30 offset0:52 offset1:188
	ds_read_b128 v[30:33], v59 offset:64112
	s_waitcnt lgkmcnt(1)
	v_mov_b32_e32 v39, v40
	ds_read_b32 v40, v54 offset:7888
	s_waitcnt lgkmcnt(1)
	v_pk_mul_f32 v[30:31], v[30:31], v[38:39]
	s_nop 0
	v_add_f32_e32 v30, v36, v30
	v_add_f32_e32 v36, v30, v31
	s_waitcnt lgkmcnt(0)
	v_pk_mul_f32 v[30:31], v[32:33], v[40:41]
	v_lshlrev_b32_e32 v32, 2, v48
	v_add_f32_e32 v30, v36, v30
	v_add_f32_e32 v30, v30, v31
	v_mul_u32_u24_e32 v31, 0x44, v58
	v_add3_u32 v29, v29, v31, v32
	ds_write_b32 v29, v30 offset:36864
	v_add_u32_e32 v29, 0x200, v28
	v_mov_b32_e32 v28, v29
	s_andn2_b64 exec, exec, s[50:51]
	s_cbranch_execnz .LBB0_1436

.LBB0_1439:
	v_ashrrev_i32_e32 v28, 8, v27
	v_bfe_u32 v29, v27, 4, 4
	v_lshl_or_b32 v29, v28, 4, v29
	v_mul_lo_u32 v29, v29, s36
	s_add_i32 s0, 0, 0x11c00
	v_lshlrev_b32_e32 v30, 6, v28
	v_mad_i32_i24 v32, v28, s18, v26
	v_add3_u32 v36, v29, s0, v30
	ds_read_b128 v[28:31], v36 offset:8832
	ds_read_b128 v[38:41], v36 offset:8848
	ds_read_b128 v[42:45], v36 offset:8864
	ds_read_b128 v[50:53], v36 offset:8880
	v_add_u32_e32 v54, 0x9000, v32
	s_nop 0
	s_nop 0
	s_nop 0
	s_nop 0
	ds_read2_b32 v[32:33], v54 offset1:17
	v_cmp_lt_i32_e32 vcc, -1, v27
	s_or_b64 s[42:43], vcc, s[42:43]
	s_waitcnt lgkmcnt(0)
	ds_read2_b32 v[80:81], v54 offset0:34 offset1:51
	v_fma_f32 v32, v28, v32, 0
	v_fmac_f32_e32 v32, v29, v33
	s_nop 0
	s_waitcnt lgkmcnt(0)
	ds_read2_b32 v[84:85], v54 offset0:68 offset1:85
	v_fmac_f32_e32 v32, v30, v80
	v_fmac_f32_e32 v32, v31, v81
	s_nop 0
	s_waitcnt lgkmcnt(0)
	ds_read2_b32 v[80:81], v54 offset0:102 offset1:119
	ds_read2_b32 v[88:89], v54 offset0:136 offset1:153
	v_pk_mul_f32 v[28:29], v[38:39], v[84:85]
	s_nop 0
	v_add_f32_e32 v28, v32, v28
	v_add_f32_e32 v30, v28, v29
	s_nop 0
	s_waitcnt lgkmcnt(1)
	ds_read2_b32 v[84:85], v54 offset0:170 offset1:187
	v_pk_mul_f32 v[28:29], v[40:41], v[80:81]
	s_nop 0
	v_add_f32_e32 v28, v30, v28
	v_add_f32_e32 v30, v28, v29
	s_nop 0
	s_waitcnt lgkmcnt(1)
	ds_read2_b32 v[80:81], v54 offset0:204 offset1:221
	ds_read2_b32 v[92:93], v54 offset0:238 offset1:255
	v_pk_mul_f32 v[28:29], v[42:43], v[88:89]
	s_nop 0
	v_add_f32_e32 v28, v30, v28
	v_add_f32_e32 v30, v28, v29
	s_nop 0
	s_waitcnt lgkmcnt(2)
	v_pk_mul_f32 v[28:29], v[44:45], v[84:85]
	s_nop 0
	v_add_f32_e32 v28, v30, v28
	v_add_f32_e32 v30, v28, v29
	s_nop 0
	s_waitcnt lgkmcnt(1)
	v_pk_mul_f32 v[28:29], v[50:51], v[80:81]
	s_nop 0
	v_add_f32_e32 v28, v30, v28
	v_add_f32_e32 v30, v28, v29
	s_nop 0
	s_waitcnt lgkmcnt(0)
	v_pk_mul_f32 v[28:29], v[52:53], v[92:93]
	s_nop 0
	v_add_f32_e32 v28, v30, v28
	v_add_f32_e32 v28, v28, v29
	v_xor_b32_e32 v28, 0x80000000, v28
	v_lshl_add_u32 v29, v48, 2, v36
	ds_write_b32 v29, v28 offset:8704
	v_add_u32_e32 v28, 0x200, v27
	v_mov_b32_e32 v27, v28
	s_andn2_b64 exec, exec, s[42:43]
	s_cbranch_execnz .LBB0_1439

.LBB0_1442:
	v_ashrrev_i32_e32 v58, 8, v28
	v_bfe_u32 v59, v28, 4, 4
	v_lshlrev_b32_e32 v29, 4, v58
	v_or_b32_e32 v30, v29, v59
	v_mul_lo_u32 v30, v30, s36
	v_lshlrev_b32_e32 v31, 6, v58
	v_add_u32_e32 v30, 0, v30
	v_add_u32_e32 v36, v27, v31
	s_movk_i32 s0, 0x3300
	v_add3_u32 v60, v30, v31, s0
	ds_read_b128 v[30:33], v60 offset:55296
	ds_read_b128 v[38:41], v60 offset:55312
	ds_read_b128 v[42:45], v60 offset:55328
	ds_read_b128 v[50:53], v60 offset:55344
	v_mad_i32_i24 v61, v58, s37, v36
	s_nop 0
	s_nop 0
	s_nop 0
	s_nop 0
	ds_read_b32 v54, v61
	v_or_b32_e32 v29, 1, v29
	v_cmp_lt_i32_e64 s[42:43], s88, v28
	s_or_b64 s[50:51], s[42:43], s[50:51]
	s_waitcnt lgkmcnt(0)
	v_fma_f32 v62, v30, v54, 0
	v_mad_u64_u32 v[54:55], s[8:9], v29, s36, v[36:37]
	ds_read2_b32 v[56:57], v54 offset1:68
	ds_read2_b32 v[80:81], v54 offset0:136 offset1:204
	v_add_u32_e32 v29, 0x400, v54
	s_waitcnt lgkmcnt(1)
	v_fmac_f32_e32 v62, v31, v56
	s_nop 0
	v_fmac_f32_e32 v62, v32, v57
	s_waitcnt lgkmcnt(0)
	ds_read2_b32 v[84:85], v29 offset0:16 offset1:84
	v_fmac_f32_e32 v62, v33, v80
	ds_read2_b32 v[88:89], v29 offset0:152 offset1:220
	v_fmac_f32_e32 v62, v38, v81
	s_nop 0
	s_waitcnt lgkmcnt(1)
	v_fmac_f32_e32 v62, v39, v84
	v_fmac_f32_e32 v62, v40, v85
	s_nop 0
	v_add_u32_e32 v29, 0x800, v54
	ds_read2_b32 v[80:81], v29 offset0:32 offset1:100
	s_waitcnt lgkmcnt(1)
	ds_read2_b32 v[84:85], v29 offset0:168 offset1:236
	v_fmac_f32_e32 v62, v41, v88
	v_fmac_f32_e32 v62, v42, v89
	s_nop 0
	s_waitcnt lgkmcnt(1)
	v_fmac_f32_e32 v62, v43, v80
	v_fmac_f32_e32 v62, v44, v81
	s_nop 0
	v_add_u32_e32 v29, 0xc00, v54
	ds_read2_b32 v[38:39], v29 offset0:184 offset1:252
	ds_read2_b32 v[80:81], v29 offset0:48 offset1:116
	ds_read_b128 v[88:91], v60 offset:55360
	s_waitcnt lgkmcnt(3)
	v_fmac_f32_e32 v62, v45, v84
	v_fmac_f32_e32 v62, v50, v85
	s_nop 0
	v_add_u32_e32 v29, 0x1000, v54
	ds_read2_b32 v[84:85], v29 offset0:64 offset1:132
	s_waitcnt lgkmcnt(2)
	v_fmac_f32_e32 v62, v51, v80
	v_fmac_f32_e32 v62, v52, v81
	s_nop 0
	v_fmac_f32_e32 v62, v53, v38
	s_waitcnt lgkmcnt(1)
	v_fmac_f32_e32 v62, v88, v39
	s_nop 0
	v_add_u32_e32 v29, 0x1200, v54
	ds_read2_b32 v[80:81], v29 offset0:72 offset1:140
	ds_read_b128 v[92:95], v60 offset:55376
	s_waitcnt lgkmcnt(2)
	v_fmac_f32_e32 v62, v89, v84
	v_fmac_f32_e32 v62, v90, v85
	s_nop 0
	v_add_u32_e32 v29, 0x1400, v54
	ds_read2_b32 v[84:85], v29 offset0:80 offset1:148
	s_waitcnt lgkmcnt(2)
	v_fmac_f32_e32 v62, v91, v80
	s_nop 0
	s_waitcnt lgkmcnt(1)
	v_fmac_f32_e32 v62, v92, v81
	s_nop 0
	v_add_u32_e32 v29, 0x1600, v54
	ds_read2_b32 v[80:81], v29 offset0:88 offset1:156
	ds_read_b128 v[88:91], v60 offset:55392
	s_waitcnt lgkmcnt(2)
	v_fmac_f32_e32 v62, v93, v84
	v_fmac_f32_e32 v62, v94, v85
	s_nop 0
	v_add_u32_e32 v29, 0x1800, v54
	ds_read2_b32 v[84:85], v29 offset0:96 offset1:164
	s_waitcnt lgkmcnt(2)
	v_fmac_f32_e32 v62, v95, v80
	s_nop 0
	s_waitcnt lgkmcnt(1)
	v_fmac_f32_e32 v62, v88, v81
	s_nop 0
	v_add_u32_e32 v29, 0x1a00, v54
	ds_read2_b32 v[80:81], v29 offset0:104 offset1:172
	ds_read_b128 v[92:95], v60 offset:55408
	s_waitcnt lgkmcnt(2)
	v_fmac_f32_e32 v62, v89, v84
	v_fmac_f32_e32 v62, v90, v85
	s_nop 0
	v_add_u32_e32 v29, 0x1c00, v54
	ds_read2_b32 v[84:85], v29 offset0:112 offset1:180
	s_waitcnt lgkmcnt(2)
	v_fmac_f32_e32 v62, v91, v80
	s_nop 0
	s_waitcnt lgkmcnt(1)
	v_fmac_f32_e32 v62, v92, v81
	s_nop 0
	v_add_u32_e32 v29, 0x1e00, v54
	ds_read2_b32 v[80:81], v29 offset0:120 offset1:188
	ds_read_b128 v[88:91], v60 offset:55424
	s_waitcnt lgkmcnt(2)
	v_fmac_f32_e32 v62, v93, v84
	v_fmac_f32_e32 v62, v94, v85
	s_nop 0
	v_add_u32_e32 v29, 0x2000, v54
	ds_read2_b32 v[84:85], v29 offset0:128 offset1:196
	s_waitcnt lgkmcnt(2)
	v_fmac_f32_e32 v62, v95, v80
	s_nop 0
	s_waitcnt lgkmcnt(1)
	v_fmac_f32_e32 v62, v88, v81
	s_nop 0
	v_add_u32_e32 v29, 0x2400, v54
	ds_read2_b32 v[80:81], v29 offset0:8 offset1:76
	s_waitcnt lgkmcnt(1)
	v_fmac_f32_e32 v62, v89, v84
	v_fmac_f32_e32 v62, v90, v85
	s_nop 0
	v_add_u32_e32 v29, 0x2600, v61
	ds_read2_b32 v[40:41], v29 offset0:84 offset1:220
	ds_read_b128 v[84:87], v60 offset:55440
	s_waitcnt lgkmcnt(2)
	v_fmac_f32_e32 v62, v91, v80
	s_nop 0
	s_nop 0
	v_mov_b32_e32 v38, v81
	s_waitcnt lgkmcnt(1)
	v_mov_b32_e32 v39, v40
	s_waitcnt lgkmcnt(0)
	v_pk_mul_f32 v[30:31], v[84:85], v[38:39]
	s_nop 0
	v_add_f32_e32 v29, v62, v30
	v_add_u32_e32 v30, 0x2600, v54
	ds_read2_b32 v[38:39], v30 offset0:84 offset1:220
	v_add_f32_e32 v29, v29, v31
	s_waitcnt lgkmcnt(0)
	v_mov_b32_e32 v40, v38
	v_pk_mul_f32 v[30:31], v[86:87], v[40:41]
	v_mov_b32_e32 v38, v39
	v_add_f32_e32 v29, v29, v30
	v_add_u32_e32 v30, 0x2a00, v61
	ds_read2_b32 v[40:41], v30 offset0:100 offset1:236
	ds_read_b128 v[80:83], v60 offset:55456
	v_add_f32_e32 v29, v29, v31
	s_nop 0
	s_nop 0
	s_waitcnt lgkmcnt(1)
	v_mov_b32_e32 v39, v40
	s_waitcnt lgkmcnt(0)
	v_pk_mul_f32 v[30:31], v[80:81], v[38:39]
	s_nop 0
	v_add_f32_e32 v29, v29, v30
	v_add_u32_e32 v30, 0x2a00, v54
	ds_read2_b32 v[38:39], v30 offset0:100 offset1:236
	v_add_f32_e32 v29, v29, v31
	s_waitcnt lgkmcnt(0)
	v_mov_b32_e32 v40, v38
	v_pk_mul_f32 v[30:31], v[82:83], v[40:41]
	v_mov_b32_e32 v38, v39
	v_add_f32_e32 v29, v29, v30
	v_add_u32_e32 v30, 0x2e00, v61
	ds_read2_b32 v[40:41], v30 offset0:116 offset1:252
	ds_read_b128 v[80:83], v60 offset:55472
	v_add_f32_e32 v29, v29, v31
	s_nop 0
	s_nop 0
	s_waitcnt lgkmcnt(1)
	v_mov_b32_e32 v39, v40
	ds_read_b32 v40, v54 offset:12240
	s_waitcnt lgkmcnt(1)
	v_pk_mul_f32 v[30:31], v[80:81], v[38:39]
	s_nop 0
	v_add_f32_e32 v29, v29, v30
	v_add_f32_e32 v29, v29, v31
	s_waitcnt lgkmcnt(0)
	v_pk_mul_f32 v[30:31], v[82:83], v[40:41]
	v_lshlrev_b32_e32 v32, 2, v48
	v_add_f32_e32 v29, v29, v30
	v_add_f32_e32 v29, v29, v31
	v_mad_i32_i24 v30, v58, s18, 0
	v_mul_u32_u24_e32 v31, 0x44, v59
	v_add3_u32 v30, v30, v31, v32
	ds_write_b32 v30, v29 offset:36864
	v_add_u32_e32 v29, 0x200, v28
	v_mov_b32_e32 v28, v29
	s_andn2_b64 exec, exec, s[50:51]
	s_cbranch_execnz .LBB0_1442

.LBB0_1445:
	v_ashrrev_i32_e32 v28, 8, v27
	v_bfe_u32 v29, v27, 4, 4
	v_lshl_or_b32 v29, v28, 4, v29
	v_mul_lo_u32 v29, v29, s36
	s_add_i32 s0, 0, 0x11c00
	v_lshlrev_b32_e32 v30, 6, v28
	v_mad_i32_i24 v32, v28, s18, v26
	v_add3_u32 v36, v29, s0, v30
	ds_read_b128 v[28:31], v36 offset:13248
	ds_read_b128 v[38:41], v36 offset:13264
	ds_read_b128 v[42:45], v36 offset:13280
	ds_read_b128 v[50:53], v36 offset:13296
	v_add_u32_e32 v54, 0x9000, v32
	s_nop 0
	s_nop 0
	s_nop 0
	s_nop 0
	ds_read2_b32 v[32:33], v54 offset1:17
	v_cmp_lt_i32_e32 vcc, s88, v27
	s_or_b64 s[42:43], vcc, s[42:43]
	s_waitcnt lgkmcnt(0)
	ds_read2_b32 v[80:81], v54 offset0:34 offset1:51
	v_fma_f32 v32, v28, v32, 0
	v_fmac_f32_e32 v32, v29, v33
	s_nop 0
	s_waitcnt lgkmcnt(0)
	ds_read2_b32 v[84:85], v54 offset0:68 offset1:85
	v_fmac_f32_e32 v32, v30, v80
	v_fmac_f32_e32 v32, v31, v81
	s_nop 0
	s_waitcnt lgkmcnt(0)
	ds_read2_b32 v[80:81], v54 offset0:102 offset1:119
	ds_read2_b32 v[88:89], v54 offset0:136 offset1:153
	v_pk_mul_f32 v[28:29], v[38:39], v[84:85]
	s_nop 0
	v_add_f32_e32 v28, v32, v28
	v_add_f32_e32 v30, v28, v29
	s_nop 0
	s_waitcnt lgkmcnt(1)
	ds_read2_b32 v[84:85], v54 offset0:170 offset1:187
	v_pk_mul_f32 v[28:29], v[40:41], v[80:81]
	s_nop 0
	v_add_f32_e32 v28, v30, v28
	v_add_f32_e32 v30, v28, v29
	s_nop 0
	s_waitcnt lgkmcnt(1)
	ds_read2_b32 v[80:81], v54 offset0:204 offset1:221
	ds_read2_b32 v[92:93], v54 offset0:238 offset1:255
	v_pk_mul_f32 v[28:29], v[42:43], v[88:89]
	s_nop 0
	v_add_f32_e32 v28, v30, v28
	v_add_f32_e32 v30, v28, v29
	s_nop 0
	s_waitcnt lgkmcnt(2)
	v_pk_mul_f32 v[28:29], v[44:45], v[84:85]
	s_nop 0
	v_add_f32_e32 v28, v30, v28
	v_add_f32_e32 v30, v28, v29
	s_nop 0
	s_waitcnt lgkmcnt(1)
	v_pk_mul_f32 v[28:29], v[50:51], v[80:81]
	s_nop 0
	v_add_f32_e32 v28, v30, v28
	v_add_f32_e32 v30, v28, v29
	s_nop 0
	s_waitcnt lgkmcnt(0)
	v_pk_mul_f32 v[28:29], v[52:53], v[92:93]
	s_nop 0
	v_add_f32_e32 v28, v30, v28
	v_add_f32_e32 v28, v28, v29
	v_xor_b32_e32 v28, 0x80000000, v28
	v_lshl_add_u32 v29, v48, 2, v36
	ds_write_b32 v29, v28 offset:13056
	v_add_u32_e32 v28, 0x200, v27
	v_mov_b32_e32 v27, v28
	s_andn2_b64 exec, exec, s[42:43]
	s_cbranch_execnz .LBB0_1445

.LBB0_1457:
	s_cmpk_lt_i32 s69, 0x400
	s_cbranch_scc1 .LBB0_1456
	s_cmpk_gt_u32 s69, 0x5ff
	s_mov_b64 s[6:7], -1
	s_cbranch_scc0 .LBB0_1471
	s_add_i32 s8, s69, 0xfffffa00
	v_mov_b32_e32 v50, v0
	s_lshr_b32 s53, s8, 2
	s_mul_i32 s60, s53, 0x30000
	v_readfirstlane_b32 s9, v50
	s_ashr_i32 s6, s9, 6
	s_and_b32 s7, s69, 3
	s_lshl_b64 s[58:59], s[60:61], 1
	s_add_u32 s0, s2, s58
	s_addc_u32 s1, s3, s59
	s_lshl_b32 s52, s7, 8
	s_add_u32 s52, s0, s52
	v_add_u32_e32 v22, 0x200, v50
	s_addc_u32 s60, s1, 0
	v_ashrrev_i32_e32 v18, 31, v50
	v_ashrrev_i32_e32 v23, 31, v22
	s_add_u32 s58, s52, 0x1000
	v_lshrrev_b32_e32 v2, 28, v18
	v_lshrrev_b32_e32 v8, 28, v23
	s_addc_u32 s59, s60, 0
	v_add_u32_e32 v2, v50, v2
	v_add_u32_e32 v8, v22, v8
	v_ashrrev_i32_e32 v54, 4, v2
	v_mov_b64_e32 v[6:7], s[58:59]
	v_ashrrev_i32_e32 v56, 4, v8
	v_and_b32_e32 v2, -16, v2
	v_mad_i64_i32 v[4:5], s[58:59], v54, s19, v[6:7]
	v_mad_i64_i32 v[6:7], s[58:59], v56, s19, v[6:7]
	v_sub_u32_e32 v55, v50, v2
	s_add_u32 s58, s52, 0x1400
	v_lshlrev_b32_e32 v2, 3, v55
	v_and_b32_e32 v8, -16, v8
	s_addc_u32 s59, s60, 0
	v_ashrrev_i32_e32 v3, 31, v2
	v_sub_u32_e32 v57, v22, v8
	v_mov_b64_e32 v[16:17], s[58:59]
	v_lshrrev_b32_e32 v18, 26, v18
	v_lshlrev_b64 v[10:11], 1, v[2:3]
	v_lshlrev_b32_e32 v8, 3, v57
	v_mad_i64_i32 v[12:13], s[58:59], v54, s19, v[16:17]
	v_mad_i64_i32 v[16:17], s[58:59], v56, s19, v[16:17]
	s_lshl_b32 s52, s7, 10
	v_add_u32_e32 v18, v50, v18
	v_lshl_add_u64 v[2:3], v[4:5], 0, v[10:11]
	v_ashrrev_i32_e32 v9, 31, v8
	s_add_u32 s58, s0, s52
	v_ashrrev_i32_e32 v58, 6, v18
	v_and_b32_e32 v18, 0xffffffc0, v18
	v_lshrrev_b32_e32 v23, 26, v23
	v_add_u32_e32 v26, 0x400, v50
	global_load_dwordx4 v[2:5], v[2:3], off
	v_lshlrev_b64 v[14:15], 1, v[8:9]
	s_addc_u32 s59, s1, 0
	v_sub_u32_e32 v59, v50, v18
	v_add_u32_e32 v23, v22, v23
	v_ashrrev_i32_e32 v27, 31, v26
	v_lshl_add_u64 v[6:7], v[6:7], 0, v[14:15]
	v_lshlrev_b32_e32 v18, 3, v59
	s_waitcnt vmcnt(0)
	v_mov_b64_e32 v[46:47], s[58:59]
	v_ashrrev_i32_e32 v60, 6, v23
	v_and_b32_e32 v23, 0xffffffc0, v23
	v_lshrrev_b32_e32 v27, 26, v27
	v_add_u32_e32 v30, 0x600, v50
	global_load_dwordx4 v[6:9], v[6:7], off
	v_lshl_add_u64 v[10:11], v[12:13], 0, v[10:11]
	v_mad_i64_i32 v[20:21], s[58:59], v58, s19, v[46:47]
	v_ashrrev_i32_e32 v19, 31, v18
	v_sub_u32_e32 v61, v22, v23
	v_add_u32_e32 v27, v26, v27
	v_ashrrev_i32_e32 v31, 31, v30
	global_load_dwordx4 v[10:13], v[10:11], off
	v_lshl_add_u64 v[14:15], v[16:17], 0, v[14:15]
	v_lshl_add_u64 v[18:19], v[18:19], 1, v[20:21]
	v_lshlrev_b32_e32 v22, 3, v61
	v_ashrrev_i32_e32 v62, 6, v27
	v_and_b32_e32 v27, 0xffffffc0, v27
	v_lshrrev_b32_e32 v31, 26, v31
	v_add_u32_e32 v34, 0x800, v50
	global_load_dwordx4 v[14:17], v[14:15], off
	v_mad_i64_i32 v[24:25], s[58:59], v60, s19, v[46:47]
	global_load_dwordx4 v[18:21], v[18:19], off
	v_ashrrev_i32_e32 v23, 31, v22
	v_sub_u32_e32 v63, v26, v27
	v_add_u32_e32 v31, v30, v31
	v_ashrrev_i32_e32 v35, 31, v34
	v_lshl_add_u64 v[22:23], v[22:23], 1, v[24:25]
	v_lshlrev_b32_e32 v26, 3, v63
	v_ashrrev_i32_e32 v64, 6, v31
	v_and_b32_e32 v31, 0xffffffc0, v31
	v_lshrrev_b32_e32 v35, 26, v35
	v_add_u32_e32 v38, 0xa00, v50
	global_load_dwordx4 v[22:25], v[22:23], off
	v_mad_i64_i32 v[28:29], s[58:59], v62, s19, v[46:47]
	v_ashrrev_i32_e32 v27, 31, v26
	v_sub_u32_e32 v65, v30, v31
	v_add_u32_e32 v35, v34, v35
	v_ashrrev_i32_e32 v39, 31, v38
	v_lshl_add_u64 v[26:27], v[26:27], 1, v[28:29]
	v_lshlrev_b32_e32 v30, 3, v65
	v_ashrrev_i32_e32 v66, 6, v35
	v_and_b32_e32 v35, 0xffffffc0, v35
	v_lshrrev_b32_e32 v39, 26, v39
	v_add_u32_e32 v42, 0xc00, v50
	global_load_dwordx4 v[26:29], v[26:27], off
	v_mad_i64_i32 v[32:33], s[58:59], v64, s19, v[46:47]
	v_ashrrev_i32_e32 v31, 31, v30
	v_sub_u32_e32 v67, v34, v35
	v_add_u32_e32 v39, v38, v39
	v_ashrrev_i32_e32 v43, 31, v42
	v_lshl_add_u64 v[30:31], v[30:31], 1, v[32:33]
	v_lshlrev_b32_e32 v34, 3, v67
	v_ashrrev_i32_e32 v68, 6, v39
	v_and_b32_e32 v39, 0xffffffc0, v39
	v_lshrrev_b32_e32 v43, 26, v43
	v_add_u32_e32 v48, 0xe00, v50
	global_load_dwordx4 v[30:33], v[30:31], off
	v_mad_i64_i32 v[36:37], s[58:59], v66, s19, v[46:47]
	v_ashrrev_i32_e32 v35, 31, v34
	v_sub_u32_e32 v69, v38, v39
	v_add_u32_e32 v43, v42, v43
	v_ashrrev_i32_e32 v49, 31, v48
	v_lshl_add_u64 v[34:35], v[34:35], 1, v[36:37]
	v_lshlrev_b32_e32 v38, 3, v69
	v_ashrrev_i32_e32 v70, 6, v43
	v_and_b32_e32 v43, 0xffffffc0, v43
	v_lshrrev_b32_e32 v49, 26, v49
	global_load_dwordx4 v[34:37], v[34:35], off
	v_mad_i64_i32 v[40:41], s[58:59], v68, s19, v[46:47]
	v_ashrrev_i32_e32 v39, 31, v38
	v_sub_u32_e32 v71, v42, v43
	v_add_u32_e32 v49, v48, v49
	v_lshl_add_u64 v[38:39], v[38:39], 1, v[40:41]
	v_lshlrev_b32_e32 v42, 3, v71
	v_ashrrev_i32_e32 v72, 6, v49
	v_and_b32_e32 v49, 0xffffffc0, v49
	global_load_dwordx4 v[38:41], v[38:39], off
	v_mad_i64_i32 v[44:45], s[58:59], v70, s19, v[46:47]
	v_ashrrev_i32_e32 v43, 31, v42
	v_sub_u32_e32 v73, v48, v49
	v_lshl_add_u64 v[42:43], v[42:43], 1, v[44:45]
	v_lshlrev_b32_e32 v48, 3, v73
	global_load_dwordx4 v[42:45], v[42:43], off
	v_mad_i64_i32 v[46:47], s[58:59], v72, s19, v[46:47]
	v_ashrrev_i32_e32 v49, 31, v48
	v_lshl_add_u64 v[46:47], v[48:49], 1, v[46:47]
	global_load_dwordx4 v[46:49], v[46:47], off
	v_and_b32_e32 v51, 63, v50
	s_lshl_b32 s0, s53, 11
	v_lshl_or_b32 v52, v51, 5, s0
	s_lshl_b32 s52, s7, 3
	v_or_b32_e32 v196, s52, v52
	s_ashr_i32 s7, s6, 31
	v_lshl_add_u64 v[52:53], v[196:197], 2, s[38:39]
	v_lshl_add_u64 v[52:53], s[6:7], 2, v[52:53]
	s_movk_i32 s1, 0x120
	global_load_dword v52, v[52:53], off
	v_mul_lo_u32 v53, v54, s1
	v_lshlrev_b32_e32 v54, 4, v55
	v_add3_u32 v53, 0, v53, v54
	ds_write_b128 v53, v[2:5]
	v_mul_lo_u32 v2, v56, s1
	v_lshlrev_b32_e32 v3, 4, v57
	v_add3_u32 v2, 0, v2, v3
	s_movk_i32 s0, 0x410
	s_waitcnt vmcnt(11)
	ds_write_b128 v2, v[6:9]
	s_waitcnt vmcnt(10)
	ds_write_b128 v53, v[10:13] offset:18432
	s_waitcnt vmcnt(9)
	ds_write_b128 v2, v[14:17] offset:18432
	v_mul_lo_u32 v2, v58, s0
	v_lshlrev_b32_e32 v3, 4, v59
	v_add3_u32 v2, 0, v2, v3
	s_waitcnt vmcnt(8)
	ds_write_b128 v2, v[18:21] offset:36864
	v_mul_lo_u32 v2, v60, s0
	v_lshlrev_b32_e32 v3, 4, v61
	v_add3_u32 v2, 0, v2, v3
	s_waitcnt vmcnt(7)
	ds_write_b128 v2, v[22:25] offset:36864
	v_mul_lo_u32 v2, v62, s0
	v_lshlrev_b32_e32 v3, 4, v63
	v_add3_u32 v2, 0, v2, v3
	v_lshlrev_b32_e32 v3, 4, v65
	s_add_i32 s58, s6, s52
	s_waitcnt vmcnt(6)
	ds_write_b128 v2, v[26:29] offset:36864
	v_mul_lo_u32 v2, v64, s0
	v_add3_u32 v2, 0, v2, v3
	v_lshlrev_b32_e32 v3, 4, v67
	s_add_i32 s62, s58, s10
	s_ashr_i32 s63, s62, 31
	s_lshl_b32 s7, s53, 5
	s_lshl_b64 s[62:63], s[62:63], 2
	s_add_u32 s62, s4, s62
	s_addc_u32 s63, s5, s63
	v_add_u32_e32 v4, -1, v226
	v_cmp_lt_i32_e32 vcc, v4, v236
	s_add_i32 s58, s58, s7
	s_waitcnt vmcnt(5)
	ds_write_b128 v2, v[30:33] offset:36864
	v_mul_lo_u32 v2, v66, s0
	v_add3_u32 v2, 0, v2, v3
	v_lshlrev_b32_e32 v3, 4, v69
	v_cndmask_b32_e32 v4, v4, v226, vcc
	v_lshlrev_b32_e32 v4, 2, v4
	v_cmp_eq_u32_e32 vcc, 0, v51
	s_ashr_i32 s59, s58, 31
	s_lshl_b64 s[58:59], s[58:59], 8
	v_and_b32_e32 v11, 15, v50
	s_movk_i32 s60, 0x120
	s_waitcnt vmcnt(4)
	ds_write_b128 v2, v[34:37] offset:36864
	v_mul_lo_u32 v2, v68, s0
	v_add3_u32 v2, 0, v2, v3
	v_lshlrev_b32_e32 v3, 4, v71
	s_waitcnt vmcnt(3)
	ds_write_b128 v2, v[38:41] offset:36864
	v_mul_lo_u32 v2, v70, s0
	v_add3_u32 v2, 0, v2, v3
	v_lshlrev_b32_e32 v3, 4, v73
	s_waitcnt vmcnt(2)
	ds_write_b128 v2, v[42:45] offset:36864
	v_mul_lo_u32 v2, v72, s0
	v_add3_u32 v2, 0, v2, v3
	s_and_b32 s0, s9, 0x3fffffc0
	s_ashr_i32 s9, s9, 7
	s_waitcnt vmcnt(1)
	ds_write_b128 v2, v[46:49] offset:36864
	global_load_dword v2, v197, s[62:63]
	s_lshl_b32 s53, s9, 4
	s_waitcnt vmcnt(0)
	v_mul_f32_e32 v2, 0x3fb8aa3b, v2
	v_exp_f32_e32 v2, v2
	s_nop 0
	v_mul_f32_e64 v3, v52, -v2
	ds_bpermute_b32 v4, v4, v3
	s_waitcnt lgkmcnt(0)
	v_fma_f32 v2, v52, -v2, v4
	v_cndmask_b32_e32 v2, v2, v3, vcc
	v_add_u32_e32 v3, -2, v226
	v_cmp_lt_i32_e32 vcc, v3, v236
	s_nop 1
	v_cndmask_b32_e32 v3, v3, v226, vcc
	v_lshlrev_b32_e32 v3, 2, v3
	ds_bpermute_b32 v3, v3, v2
	v_cmp_gt_u32_e32 vcc, 2, v51
	s_waitcnt lgkmcnt(0)
	v_add_f32_e32 v3, v2, v3
	v_cndmask_b32_e32 v2, v3, v2, vcc
	v_add_u32_e32 v3, -4, v226
	v_cmp_lt_i32_e32 vcc, v3, v236
	s_nop 1
	v_cndmask_b32_e32 v3, v3, v226, vcc
	v_lshlrev_b32_e32 v3, 2, v3
	ds_bpermute_b32 v3, v3, v2
	v_cmp_gt_u32_e32 vcc, 4, v51
	s_waitcnt lgkmcnt(0)
	v_add_f32_e32 v3, v2, v3
	v_cndmask_b32_e32 v2, v3, v2, vcc
	v_add_u32_e32 v3, -8, v226
	v_cmp_lt_i32_e32 vcc, v3, v236
	s_nop 1
	v_cndmask_b32_e32 v3, v3, v226, vcc
	v_lshlrev_b32_e32 v3, 2, v3
	ds_bpermute_b32 v3, v3, v2
	v_cmp_gt_u32_e32 vcc, 8, v51
	s_waitcnt lgkmcnt(0)
	v_add_f32_e32 v3, v2, v3
	v_cndmask_b32_e32 v2, v3, v2, vcc
	v_add_u32_e32 v3, -16, v226
	v_cmp_lt_i32_e32 vcc, v3, v236
	s_nop 1
	v_cndmask_b32_e32 v3, v3, v226, vcc
	v_lshlrev_b32_e32 v3, 2, v3
	ds_bpermute_b32 v3, v3, v2
	v_cmp_gt_u32_e32 vcc, 16, v51
	s_waitcnt lgkmcnt(0)
	v_add_f32_e32 v3, v2, v3
	v_cndmask_b32_e32 v2, v3, v2, vcc
	v_subrev_u32_e32 v3, 32, v226
	v_cmp_lt_i32_e32 vcc, v3, v236
	s_nop 1
	v_cndmask_b32_e32 v3, v3, v226, vcc
	v_lshlrev_b32_e32 v3, 2, v3
	ds_bpermute_b32 v3, v3, v2
	v_cmp_gt_u32_e32 vcc, 32, v51
	s_waitcnt lgkmcnt(0)
	v_add_f32_e32 v3, v2, v3
	v_cndmask_b32_e32 v2, v3, v2, vcc
	v_bfrev_b32_e32 v3, 0.5
	v_lshl_or_b32 v3, v226, 2, v3
	ds_bpermute_b32 v6, v3, v2
	v_or_b32_e32 v3, s0, v51
	v_lshl_add_u32 v3, v3, 2, 0
	v_add_u32_e32 v4, 0x1d800, v3
	ds_write_b32 v4, v52
	v_add_u32_e32 v4, 0x1e000, v3
	ds_write_b32 v4, v2
	s_waitcnt lgkmcnt(2)
	v_sub_f32_e32 v4, v6, v2
	v_mul_f32_e32 v4, 0x3fb8aa3b, v4
	v_exp_f32_e32 v4, v4
	v_mul_f32_e32 v2, 0x3fb8aa3b, v2
	v_exp_f32_e32 v7, v2
	v_add_u32_e32 v3, 0x1e800, v3
	ds_write_b32 v3, v4
	v_lshl_or_b32 v2, v51, 2, s58
	v_mov_b32_e32 v3, s59
	v_lshl_add_u64 v[4:5], s[40:41], 0, v[2:3]
	global_store_dword v[4:5], v7, off
	v_mul_f32_e32 v4, 0x3fb8aa3b, v6
	v_exp_f32_e32 v4, v4
	v_lshl_add_u64 v[2:3], s[42:43], 0, v[2:3]
	s_lshl_b32 s0, s6, 1
	s_and_b32 s6, s0, 2
	global_store_dword v[2:3], v4, off
	s_waitcnt lgkmcnt(0)
	s_barrier
	v_and_b32_e32 v3, 48, v50
	v_or_b32_e32 v2, s53, v11
	v_add_u32_e32 v10, 0, v3
	v_mad_u64_u32 v[8:9], s[58:59], v2, s1, v[10:11]
	v_mov_b32_e32 v2, 0
	s_cmp_gt_i32 s6, s9
	v_mov_b32_e32 v4, 0
	v_mov_b32_e32 v5, 0
	v_mov_b32_e32 v6, 0
	v_mov_b32_e32 v7, 0
	s_cbranch_scc1 .LBB0_1461
	ds_read_b128 v[4:7], v8 offset:18432
	v_lshl_or_b32 v3, s6, 4, v11
	v_mad_u32_u24 v3, v3, s60, v10
	ds_read_b128 v[12:15], v3
	ds_read_b128 v[80:83], v8 offset:18496
	ds_read_b128 v[16:19], v3 offset:64
	s_nop 0
	s_nop 0
	s_waitcnt lgkmcnt(2)
	ds_read_b128 v[84:87], v8 offset:18560
	ds_read_b128 v[88:91], v3 offset:128
	v_mfma_f32_16x16x32_bf16 v[4:7], v[4:7], v[12:15], 0
	s_nop 0
	s_nop 0
	s_waitcnt lgkmcnt(2)
	ds_read_b128 v[92:95], v8 offset:18624
	ds_read_b128 v[96:99], v3 offset:192
	v_mfma_f32_16x16x32_bf16 v[4:7], v[80:83], v[16:19], v[4:7]
	s_nop 0
	s_nop 0
	s_waitcnt lgkmcnt(2)
	v_mfma_f32_16x16x32_bf16 v[4:7], v[84:87], v[88:91], v[4:7]
	s_nop 0
	s_nop 0
	s_waitcnt lgkmcnt(0)
	v_mfma_f32_16x16x32_bf16 v[4:7], v[92:95], v[96:99], v[4:7]
.LBB0_1461:
	v_lshrrev_b32_e32 v3, 2, v50
	v_and_or_b32 v3, v3, 12, s53
	v_readlane_b32 s1, v253, 15
	s_lshl_b32 s0, s6, 6
	v_mul_lo_u32 v12, v3, s36
	v_lshl_add_u32 v9, v11, 2, s1
	v_add3_u32 v3, v9, s0, v12
	s_or_b32 s53, s6, 1
	ds_write2_b32 v3, v4, v5 offset1:68
	ds_write2_b32 v3, v6, v7 offset0:136 offset1:204
	s_cmp_ge_i32 s6, s9
	v_mov_b32_e32 v3, 0
	v_mov_b32_e32 v4, 0
	v_mov_b32_e32 v5, 0
	s_cbranch_scc1 .LBB0_1463
	ds_read_b128 v[80:83], v8 offset:18432
	v_lshl_or_b32 v2, s53, 4, v11
	v_mad_u32_u24 v6, v2, s60, v10
	ds_read_b128 v[14:17], v6
	ds_read_b128 v[84:87], v8 offset:18496
	ds_read_b128 v[18:21], v6 offset:64
	s_nop 0
	s_nop 0
	s_waitcnt lgkmcnt(2)
	ds_read_b128 v[88:91], v8 offset:18560
	ds_read_b128 v[92:95], v6 offset:128
	v_mfma_f32_16x16x32_bf16 v[2:5], v[80:83], v[14:17], 0
	s_nop 0
	s_nop 0
	s_waitcnt lgkmcnt(2)
	ds_read_b128 v[80:83], v8 offset:18624
	ds_read_b128 v[96:99], v6 offset:192
	v_mfma_f32_16x16x32_bf16 v[2:5], v[84:87], v[18:21], v[2:5]
	s_nop 0
	s_nop 0
	s_waitcnt lgkmcnt(2)
	v_mfma_f32_16x16x32_bf16 v[2:5], v[88:91], v[92:95], v[2:5]
	s_nop 0
	s_nop 0
	s_waitcnt lgkmcnt(0)
	v_mfma_f32_16x16x32_bf16 v[2:5], v[80:83], v[96:99], v[2:5]
.LBB0_1463:
	s_lshl_b32 s0, s53, 6
	v_ashrrev_i32_e32 v24, 2, v50
	v_lshlrev_b32_e32 v26, 1, v50
	v_add3_u32 v6, v9, s0, v12
	v_and_b32_e32 v14, -8, v24
	v_and_b32_e32 v27, 62, v26
	s_nop 1
	ds_write2_b32 v6, v2, v3 offset1:68
	ds_write2_b32 v6, v4, v5 offset0:136 offset1:204
	v_mul_u32_u24_e32 v2, 0x120, v27
	v_lshlrev_b32_e32 v3, 1, v14
	v_add3_u32 v8, 0, v2, v3
	ds_read_b128 v[2:5], v8
	ds_read_b128 v[80:83], v8 offset:288
	s_lshl_b32 s0, s8, 14
	s_add_u32 s8, s11, s0
	s_addc_u32 s9, s26, 0
	v_lshlrev_b32_e32 v196, 1, v27
	s_waitcnt lgkmcnt(1)
	v_lshlrev_b32_e32 v9, 16, v2
	v_and_b32_e32 v10, 0xffff0000, v2
	v_lshlrev_b32_e32 v11, 16, v3
	v_and_b32_e32 v12, 0xffff0000, v3
	v_lshlrev_b32_e32 v13, 16, v4
	v_and_b32_e32 v16, 0xffff0000, v4
	v_lshlrev_b32_e32 v17, 16, v5
	v_and_b32_e32 v18, 0xffff0000, v5
	s_nop 0
	v_lshl_add_u64 v[6:7], s[8:9], 0, v[196:197]
	s_movk_i32 s0, 0x2f0
	v_mad_u32_u24 v28, v27, s0, v8
	ds_read_b128 v[84:87], v28 offset:36864
	ds_read_b128 v[88:91], v28 offset:37904
	s_mov_b32 s0, 0x3fffffc0
	s_waitcnt lgkmcnt(2)
	v_lshlrev_b32_e32 v15, 16, v80
	v_cvt_pk_bf16_f32 v9, v9, v15
	v_ashrrev_i32_e32 v15, 31, v14
	v_and_b32_e32 v19, 0xffff0000, v80
	v_lshlrev_b32_e32 v20, 16, v81
	v_and_b32_e32 v21, 0xffff0000, v81
	v_lshlrev_b64 v[2:3], 7, v[14:15]
	v_lshl_add_u64 v[2:3], v[6:7], 0, v[2:3]
	global_store_dword v[2:3], v9, off
	v_or_b32_e32 v2, 1, v14
	v_ashrrev_i32_e32 v3, 31, v2
	v_lshlrev_b64 v[2:3], 7, v[2:3]
	v_cvt_pk_bf16_f32 v9, v10, v19
	v_lshl_add_u64 v[2:3], v[6:7], 0, v[2:3]
	global_store_dword v[2:3], v9, off
	v_or_b32_e32 v2, 2, v14
	v_ashrrev_i32_e32 v3, 31, v2
	v_lshlrev_b64 v[2:3], 7, v[2:3]
	v_cvt_pk_bf16_f32 v9, v11, v20
	v_lshl_add_u64 v[2:3], v[6:7], 0, v[2:3]
	global_store_dword v[2:3], v9, off
	v_or_b32_e32 v2, 3, v14
	v_ashrrev_i32_e32 v3, 31, v2
	v_lshlrev_b64 v[2:3], 7, v[2:3]
	v_cvt_pk_bf16_f32 v9, v12, v21
	v_lshl_add_u64 v[2:3], v[6:7], 0, v[2:3]
	global_store_dword v[2:3], v9, off
	v_or_b32_e32 v2, 4, v14
	v_ashrrev_i32_e32 v3, 31, v2
	v_lshlrev_b32_e32 v22, 16, v82
	v_lshlrev_b64 v[2:3], 7, v[2:3]
	v_cvt_pk_bf16_f32 v9, v13, v22
	v_lshl_add_u64 v[2:3], v[6:7], 0, v[2:3]
	global_store_dword v[2:3], v9, off
	v_or_b32_e32 v2, 5, v14
	v_ashrrev_i32_e32 v3, 31, v2
	v_and_b32_e32 v4, 0xffff0000, v82
	v_lshlrev_b64 v[2:3], 7, v[2:3]
	v_cvt_pk_bf16_f32 v4, v16, v4
	v_lshl_add_u64 v[2:3], v[6:7], 0, v[2:3]
	global_store_dword v[2:3], v4, off
	v_or_b32_e32 v2, 6, v14
	v_ashrrev_i32_e32 v3, 31, v2
	v_lshlrev_b32_e32 v23, 16, v83
	v_lshlrev_b64 v[2:3], 7, v[2:3]
	v_cvt_pk_bf16_f32 v4, v17, v23
	v_lshl_add_u64 v[2:3], v[6:7], 0, v[2:3]
	global_store_dword v[2:3], v4, off
	v_or_b32_e32 v2, 7, v24
	v_ashrrev_i32_e32 v3, 31, v2
	v_and_b32_e32 v5, 0xffff0000, v83
	v_lshlrev_b64 v[2:3], 7, v[2:3]
	v_cvt_pk_bf16_f32 v4, v18, v5
	v_lshl_add_u64 v[2:3], v[6:7], 0, v[2:3]
	v_and_or_b32 v15, v24, s0, v27
	global_store_dword v[2:3], v4, off
	s_or_b32 s58, s7, s52
	v_ashrrev_i32_e32 v2, 8, v50
	v_lshlrev_b32_e32 v15, 2, v15
	s_add_i32 s6, 0, 0x1d800
	v_add_u32_e32 v16, s58, v2
	s_nop 0
	s_nop 0
	v_add_u32_e32 v22, s6, v15
	ds_read_b64 v[22:23], v22
	v_ashrrev_i32_e32 v17, 31, v16
	v_lshl_add_u64 v[10:11], s[44:45], 0, v[196:197]
	v_lshlrev_b64 v[16:17], 13, v[16:17]
	s_waitcnt lgkmcnt(1)
	v_lshlrev_b32_e32 v21, 16, v88
	v_lshlrev_b32_e32 v20, 16, v84
	v_lshlrev_b32_e32 v24, 7, v24
	v_lshl_add_u64 v[12:13], s[46:47], 0, v[196:197]
	s_add_i32 s7, 0, 0x1e800
	v_lshl_add_u64 v[18:19], v[10:11], 0, v[16:17]
	s_waitcnt lgkmcnt(0)
	v_pk_mul_f32 v[20:21], v[22:23], v[20:21]
	v_and_b32_e32 v196, 0x1c00, v24
	v_add_u32_e32 v15, s7, v15
	ds_read_b64 v[80:81], v15
	ds_read_b128 v[92:95], v28 offset:37120
	ds_read_b128 v[96:99], v28 offset:38160
	v_cvt_pk_bf16_f32 v25, v20, v21
	v_lshl_add_u64 v[18:19], v[18:19], 0, v[196:197]
	global_store_dword v[18:19], v25, off
	s_nop 0
	v_lshl_add_u64 v[16:17], v[12:13], 0, v[16:17]
	v_lshl_add_u64 v[16:17], v[16:17], 0, v[196:197]
	s_waitcnt lgkmcnt(2)
	v_pk_mul_f32 v[20:21], v[80:81], v[20:21]
	s_nop 0
	v_cvt_pk_bf16_f32 v15, v20, v21
	v_and_b32_e32 v21, 0xffff0000, v88
	v_and_b32_e32 v20, 0xffff0000, v84
	v_pk_mul_f32 v[20:21], v[22:23], v[20:21]
	v_and_b32_e32 v6, 0xffff0000, v85
	v_cvt_pk_bf16_f32 v2, v20, v21
	v_pk_mul_f32 v[20:21], v[80:81], v[20:21]
	global_store_dword v[18:19], v2, off offset:128
	v_cvt_pk_bf16_f32 v2, v20, v21
	v_lshlrev_b32_e32 v21, 16, v89
	v_lshlrev_b32_e32 v20, 16, v85
	v_pk_mul_f32 v[20:21], v[22:23], v[20:21]
	global_store_dword v[16:17], v2, off offset:128
	v_cvt_pk_bf16_f32 v2, v20, v21
	v_pk_mul_f32 v[20:21], v[80:81], v[20:21]
	global_store_dword v[18:19], v2, off offset:256
	v_cvt_pk_bf16_f32 v2, v20, v21
	v_and_b32_e32 v7, 0xffff0000, v89
	global_store_dword v[16:17], v2, off offset:256
	v_pk_mul_f32 v[2:3], v[22:23], v[6:7]
	global_store_dword v[16:17], v15, off
	v_cvt_pk_bf16_f32 v6, v2, v3
	v_pk_mul_f32 v[2:3], v[80:81], v[2:3]
	global_store_dword v[18:19], v6, off offset:384
	v_cvt_pk_bf16_f32 v2, v2, v3
	global_store_dword v[16:17], v2, off offset:384
	v_lshlrev_b32_e32 v3, 16, v90
	v_lshlrev_b32_e32 v2, 16, v86
	v_pk_mul_f32 v[2:3], v[22:23], v[2:3]
	v_add_u32_e32 v15, 0x80, v14
	v_cvt_pk_bf16_f32 v6, v2, v3
	v_pk_mul_f32 v[2:3], v[80:81], v[2:3]
	global_store_dword v[18:19], v6, off offset:512
	v_cvt_pk_bf16_f32 v2, v2, v3
	global_store_dword v[16:17], v2, off offset:512
	v_and_b32_e32 v3, 0xffff0000, v90
	v_and_b32_e32 v2, 0xffff0000, v86
	v_pk_mul_f32 v[2:3], v[22:23], v[2:3]
	s_nop 0
	v_cvt_pk_bf16_f32 v4, v2, v3
	v_pk_mul_f32 v[2:3], v[80:81], v[2:3]
	global_store_dword v[18:19], v4, off offset:640
	v_cvt_pk_bf16_f32 v2, v2, v3
	global_store_dword v[16:17], v2, off offset:640
	v_lshlrev_b32_e32 v3, 16, v91
	v_lshlrev_b32_e32 v2, 16, v87
	v_pk_mul_f32 v[2:3], v[22:23], v[2:3]
	s_nop 0
	v_cvt_pk_bf16_f32 v4, v2, v3
	v_pk_mul_f32 v[2:3], v[80:81], v[2:3]
	global_store_dword v[18:19], v4, off offset:768
	v_cvt_pk_bf16_f32 v2, v2, v3
	global_store_dword v[16:17], v2, off offset:768
	v_and_b32_e32 v3, 0xffff0000, v91
	v_and_b32_e32 v2, 0xffff0000, v87
	v_pk_mul_f32 v[2:3], v[22:23], v[2:3]
	s_nop 0
	v_cvt_pk_bf16_f32 v4, v2, v3
	v_pk_mul_f32 v[2:3], v[80:81], v[2:3]
	global_store_dword v[18:19], v4, off offset:896
	v_cvt_pk_bf16_f32 v2, v2, v3
	global_store_dword v[16:17], v2, off offset:896
	v_ashrrev_i32_e32 v2, 6, v15
	v_add_u32_e32 v16, s58, v2
	v_and_or_b32 v15, v15, s0, v27
	v_ashrrev_i32_e32 v17, 31, v16
	v_lshlrev_b32_e32 v15, 2, v15
	s_nop 0
	s_nop 0
	v_add_u32_e32 v24, s6, v15
	ds_read_b64 v[80:81], v24
	v_lshlrev_b64 v[16:17], 13, v[16:17]
	v_lshl_add_u64 v[18:19], v[10:11], 0, v[16:17]
	v_lshl_add_u64 v[22:23], v[12:13], 0, v[16:17]
	s_nop 0
	s_waitcnt lgkmcnt(1)
	v_lshlrev_b32_e32 v21, 16, v96
	v_lshlrev_b32_e32 v20, 16, v92
	v_add_u32_e32 v15, s7, v15
	ds_read_b64 v[84:85], v15
	ds_read_b128 v[88:91], v28 offset:37376
	ds_read_b128 v[100:103], v28 offset:38416
	v_lshl_add_u64 v[18:19], v[18:19], 0, v[196:197]
	s_waitcnt lgkmcnt(3)
	v_pk_mul_f32 v[24:25], v[80:81], v[20:21]
	v_lshl_add_u64 v[22:23], v[22:23], 0, v[196:197]
	v_cvt_pk_bf16_f32 v20, v24, v25
	global_store_dword v[18:19], v20, off
	s_nop 0
	s_waitcnt lgkmcnt(2)
	v_pk_mul_f32 v[24:25], v[84:85], v[24:25]
	s_nop 0
	v_cvt_pk_bf16_f32 v15, v24, v25
	v_and_b32_e32 v25, 0xffff0000, v96
	v_and_b32_e32 v24, 0xffff0000, v92
	v_pk_mul_f32 v[24:25], v[80:81], v[24:25]
	v_and_b32_e32 v6, 0xffff0000, v93
	v_cvt_pk_bf16_f32 v2, v24, v25
	v_pk_mul_f32 v[24:25], v[84:85], v[24:25]
	global_store_dword v[18:19], v2, off offset:128
	v_cvt_pk_bf16_f32 v2, v24, v25
	v_lshlrev_b32_e32 v25, 16, v97
	v_lshlrev_b32_e32 v24, 16, v93
	v_pk_mul_f32 v[24:25], v[80:81], v[24:25]
	global_store_dword v[22:23], v2, off offset:128
	v_cvt_pk_bf16_f32 v2, v24, v25
	v_pk_mul_f32 v[24:25], v[84:85], v[24:25]
	global_store_dword v[18:19], v2, off offset:256
	v_cvt_pk_bf16_f32 v2, v24, v25
	v_and_b32_e32 v7, 0xffff0000, v97
	global_store_dword v[22:23], v2, off offset:256
	v_pk_mul_f32 v[2:3], v[80:81], v[6:7]
	global_store_dword v[22:23], v15, off
	v_cvt_pk_bf16_f32 v6, v2, v3
	v_pk_mul_f32 v[2:3], v[84:85], v[2:3]
	global_store_dword v[18:19], v6, off offset:384
	v_cvt_pk_bf16_f32 v2, v2, v3
	global_store_dword v[22:23], v2, off offset:384
	v_lshlrev_b32_e32 v3, 16, v98
	v_lshlrev_b32_e32 v2, 16, v94
	v_pk_mul_f32 v[2:3], v[80:81], v[2:3]
	v_add_u32_e32 v15, 0x100, v14
	v_cvt_pk_bf16_f32 v6, v2, v3
	v_pk_mul_f32 v[2:3], v[84:85], v[2:3]
	global_store_dword v[18:19], v6, off offset:512
	v_cvt_pk_bf16_f32 v2, v2, v3
	global_store_dword v[22:23], v2, off offset:512
	v_and_b32_e32 v3, 0xffff0000, v98
	v_and_b32_e32 v2, 0xffff0000, v94
	v_pk_mul_f32 v[2:3], v[80:81], v[2:3]
	s_nop 0
	v_cvt_pk_bf16_f32 v4, v2, v3
	v_pk_mul_f32 v[2:3], v[84:85], v[2:3]
	global_store_dword v[18:19], v4, off offset:640
	v_cvt_pk_bf16_f32 v2, v2, v3
	global_store_dword v[22:23], v2, off offset:640
	v_lshlrev_b32_e32 v3, 16, v99
	v_lshlrev_b32_e32 v2, 16, v95
	v_pk_mul_f32 v[2:3], v[80:81], v[2:3]
	s_nop 0
	v_cvt_pk_bf16_f32 v4, v2, v3
	v_pk_mul_f32 v[2:3], v[84:85], v[2:3]
	global_store_dword v[18:19], v4, off offset:768
	v_cvt_pk_bf16_f32 v2, v2, v3
	global_store_dword v[22:23], v2, off offset:768
	v_and_b32_e32 v3, 0xffff0000, v99
	v_and_b32_e32 v2, 0xffff0000, v95
	v_pk_mul_f32 v[2:3], v[80:81], v[2:3]
	s_nop 0
	v_cvt_pk_bf16_f32 v4, v2, v3
	v_pk_mul_f32 v[2:3], v[84:85], v[2:3]
	global_store_dword v[18:19], v4, off offset:896
	v_cvt_pk_bf16_f32 v2, v2, v3
	global_store_dword v[22:23], v2, off offset:896
	v_ashrrev_i32_e32 v2, 6, v15
	v_and_or_b32 v15, v15, s0, v27
	v_lshlrev_b32_e32 v15, 2, v15
	v_add_u32_e32 v16, s58, v2
	s_nop 0
	s_nop 0
	v_add_u32_e32 v22, s6, v15
	ds_read_b64 v[22:23], v22
	v_ashrrev_i32_e32 v17, 31, v16
	v_lshlrev_b64 v[16:17], 13, v[16:17]
	s_waitcnt lgkmcnt(1)
	v_lshlrev_b32_e32 v21, 16, v100
	v_lshlrev_b32_e32 v20, 16, v88
	v_lshl_add_u64 v[18:19], v[10:11], 0, v[16:17]
	s_waitcnt lgkmcnt(0)
	v_pk_mul_f32 v[20:21], v[22:23], v[20:21]
	v_add_u32_e32 v15, s7, v15
	ds_read_b64 v[80:81], v15
	v_cvt_pk_bf16_f32 v24, v20, v21
	v_lshl_add_u64 v[18:19], v[18:19], 0, v[196:197]
	global_store_dword v[18:19], v24, off
	s_nop 0
	v_lshl_add_u64 v[16:17], v[12:13], 0, v[16:17]
	v_lshl_add_u64 v[16:17], v[16:17], 0, v[196:197]
	s_waitcnt lgkmcnt(0)
	v_pk_mul_f32 v[20:21], v[80:81], v[20:21]
	s_nop 0
	v_cvt_pk_bf16_f32 v15, v20, v21
	v_and_b32_e32 v21, 0xffff0000, v100
	v_and_b32_e32 v20, 0xffff0000, v88
	v_pk_mul_f32 v[20:21], v[22:23], v[20:21]
	v_and_b32_e32 v6, 0xffff0000, v89
	v_cvt_pk_bf16_f32 v2, v20, v21
	v_pk_mul_f32 v[20:21], v[80:81], v[20:21]
	global_store_dword v[18:19], v2, off offset:128
	v_cvt_pk_bf16_f32 v2, v20, v21
	v_lshlrev_b32_e32 v21, 16, v101
	v_lshlrev_b32_e32 v20, 16, v89
	v_pk_mul_f32 v[20:21], v[22:23], v[20:21]
	global_store_dword v[16:17], v2, off offset:128
	v_cvt_pk_bf16_f32 v2, v20, v21
	v_pk_mul_f32 v[20:21], v[80:81], v[20:21]
	global_store_dword v[18:19], v2, off offset:256
	v_cvt_pk_bf16_f32 v2, v20, v21
	v_and_b32_e32 v7, 0xffff0000, v101
	global_store_dword v[16:17], v2, off offset:256
	v_pk_mul_f32 v[2:3], v[22:23], v[6:7]
	global_store_dword v[16:17], v15, off
	v_cvt_pk_bf16_f32 v6, v2, v3
	v_pk_mul_f32 v[2:3], v[80:81], v[2:3]
	global_store_dword v[18:19], v6, off offset:384
	v_cvt_pk_bf16_f32 v2, v2, v3
	global_store_dword v[16:17], v2, off offset:384
	v_lshlrev_b32_e32 v3, 16, v102
	v_lshlrev_b32_e32 v2, 16, v90
	v_pk_mul_f32 v[2:3], v[22:23], v[2:3]
	s_nop 0
	v_cvt_pk_bf16_f32 v6, v2, v3
	v_pk_mul_f32 v[2:3], v[80:81], v[2:3]
	global_store_dword v[18:19], v6, off offset:512
	v_cvt_pk_bf16_f32 v2, v2, v3
	global_store_dword v[16:17], v2, off offset:512
	v_and_b32_e32 v3, 0xffff0000, v102
	v_and_b32_e32 v2, 0xffff0000, v90
	v_pk_mul_f32 v[2:3], v[22:23], v[2:3]
	s_nop 0
	v_cvt_pk_bf16_f32 v4, v2, v3
	v_pk_mul_f32 v[2:3], v[80:81], v[2:3]
	global_store_dword v[18:19], v4, off offset:640
	v_cvt_pk_bf16_f32 v2, v2, v3
	global_store_dword v[16:17], v2, off offset:640
	v_lshlrev_b32_e32 v3, 16, v103
	v_lshlrev_b32_e32 v2, 16, v91
	v_pk_mul_f32 v[2:3], v[22:23], v[2:3]
	s_nop 0
	v_cvt_pk_bf16_f32 v4, v2, v3
	v_pk_mul_f32 v[2:3], v[80:81], v[2:3]
	global_store_dword v[18:19], v4, off offset:768
	v_cvt_pk_bf16_f32 v2, v2, v3
	global_store_dword v[16:17], v2, off offset:768
	v_and_b32_e32 v3, 0xffff0000, v103
	v_and_b32_e32 v2, 0xffff0000, v91
	v_pk_mul_f32 v[2:3], v[22:23], v[2:3]
	s_nop 0
	v_cvt_pk_bf16_f32 v4, v2, v3
	v_pk_mul_f32 v[2:3], v[80:81], v[2:3]
	global_store_dword v[18:19], v4, off offset:896
	v_cvt_pk_bf16_f32 v2, v2, v3
	global_store_dword v[16:17], v2, off offset:896
	v_add_u32_e32 v16, 0x180, v14
	v_ashrrev_i32_e32 v2, 6, v16
	v_add_u32_e32 v14, s58, v2
	ds_read_b128 v[2:5], v28 offset:37632
	ds_read_b128 v[6:9], v28 offset:38672
	v_and_or_b32 v16, v16, s0, v27
	v_ashrrev_i32_e32 v15, 31, v14
	v_lshlrev_b32_e32 v16, 2, v16
	s_nop 0
	s_nop 0
	v_add_u32_e32 v18, s6, v16
	ds_read_b64 v[80:81], v18
	v_lshlrev_b64 v[14:15], 13, v[14:15]
	v_lshl_add_u64 v[20:21], v[10:11], 0, v[14:15]
	s_nop 0
	v_add_u32_e32 v22, s7, v16
	ds_read_b64 v[84:85], v22
	v_lshl_add_u64 v[16:17], v[12:13], 0, v[14:15]
	s_waitcnt lgkmcnt(2)
	v_lshlrev_b32_e32 v13, 16, v6
	v_lshlrev_b32_e32 v12, 16, v2
	s_waitcnt lgkmcnt(1)
	v_pk_mul_f32 v[18:19], v[80:81], v[12:13]
	v_lshl_add_u64 v[12:13], v[20:21], 0, v[196:197]
	v_cvt_pk_bf16_f32 v14, v18, v19
	global_store_dword v[12:13], v14, off
	s_nop 0
	v_lshl_add_u64 v[16:17], v[16:17], 0, v[196:197]
	s_movk_i32 s0, 0x4000
	v_cmp_gt_i32_e32 vcc, s0, v50
	s_waitcnt lgkmcnt(0)
	v_pk_mul_f32 v[18:19], v[84:85], v[18:19]
	s_nop 0
	v_cvt_pk_bf16_f32 v18, v18, v19
	global_store_dword v[16:17], v18, off
	v_and_b32_e32 v19, 0xffff0000, v6
	v_and_b32_e32 v18, 0xffff0000, v2
	v_pk_mul_f32 v[18:19], v[80:81], v[18:19]
	v_and_b32_e32 v6, 0xffff0000, v3
	v_cvt_pk_bf16_f32 v2, v18, v19
	v_pk_mul_f32 v[18:19], v[84:85], v[18:19]
	global_store_dword v[12:13], v2, off offset:128
	v_cvt_pk_bf16_f32 v2, v18, v19
	v_lshlrev_b32_e32 v19, 16, v7
	v_lshlrev_b32_e32 v18, 16, v3
	v_pk_mul_f32 v[18:19], v[80:81], v[18:19]
	global_store_dword v[16:17], v2, off offset:128
	v_cvt_pk_bf16_f32 v2, v18, v19
	v_pk_mul_f32 v[18:19], v[84:85], v[18:19]
	global_store_dword v[12:13], v2, off offset:256
	v_cvt_pk_bf16_f32 v2, v18, v19
	v_and_b32_e32 v7, 0xffff0000, v7
	global_store_dword v[16:17], v2, off offset:256
	v_pk_mul_f32 v[2:3], v[80:81], v[6:7]
	s_nop 0
	v_cvt_pk_bf16_f32 v6, v2, v3
	v_pk_mul_f32 v[2:3], v[84:85], v[2:3]
	global_store_dword v[12:13], v6, off offset:384
	v_cvt_pk_bf16_f32 v2, v2, v3
	global_store_dword v[16:17], v2, off offset:384
	v_lshlrev_b32_e32 v3, 16, v8
	v_lshlrev_b32_e32 v2, 16, v4
	v_pk_mul_f32 v[2:3], v[80:81], v[2:3]
	s_nop 0
	v_cvt_pk_bf16_f32 v6, v2, v3
	v_pk_mul_f32 v[2:3], v[84:85], v[2:3]
	global_store_dword v[12:13], v6, off offset:512
	v_cvt_pk_bf16_f32 v2, v2, v3
	global_store_dword v[16:17], v2, off offset:512
	v_and_b32_e32 v3, 0xffff0000, v8
	v_and_b32_e32 v2, 0xffff0000, v4
	v_pk_mul_f32 v[2:3], v[80:81], v[2:3]
	s_nop 0
	v_cvt_pk_bf16_f32 v4, v2, v3
	v_pk_mul_f32 v[2:3], v[84:85], v[2:3]
	global_store_dword v[12:13], v4, off offset:640
	v_cvt_pk_bf16_f32 v2, v2, v3
	global_store_dword v[16:17], v2, off offset:640
	v_lshlrev_b32_e32 v3, 16, v9
	v_lshlrev_b32_e32 v2, 16, v5
	v_pk_mul_f32 v[2:3], v[80:81], v[2:3]
	s_nop 0
	v_cvt_pk_bf16_f32 v4, v2, v3
	v_pk_mul_f32 v[2:3], v[84:85], v[2:3]
	global_store_dword v[12:13], v4, off offset:768
	v_cvt_pk_bf16_f32 v2, v2, v3
	global_store_dword v[16:17], v2, off offset:768
	v_and_b32_e32 v3, 0xffff0000, v9
	v_and_b32_e32 v2, 0xffff0000, v5
	v_pk_mul_f32 v[2:3], v[80:81], v[2:3]
	s_nop 0
	v_cvt_pk_bf16_f32 v4, v2, v3
	v_pk_mul_f32 v[2:3], v[84:85], v[2:3]
	global_store_dword v[12:13], v4, off offset:896
	v_cvt_pk_bf16_f32 v2, v2, v3
	global_store_dword v[16:17], v2, off offset:896
	s_waitcnt lgkmcnt(0)
	s_barrier
	s_and_saveexec_b64 s[6:7], vcc
	s_cbranch_execz .LBB0_1470
	s_mov_b64 s[8:9], 0
	s_branch .LBB0_1466

.LBB0_1476:
	s_or_b64 exec, exec, s[6:7]
	s_movk_i32 s0, 0x2100
	v_mul_lo_u32 v2, v2, s0
	v_add_f32_e32 v3, v22, v4
	v_add3_u32 v2, s72, v196, v2
	v_add_f32_e32 v21, v21, v4
	ds_write2_b32 v2, v3, v21 offset1:132
	v_add_f32_e32 v3, v19, v4
	v_add_f32_e32 v19, v20, v4
	v_add_u32_e32 v20, 0x400, v2
	ds_write2_b32 v20, v3, v19 offset0:8 offset1:140
	v_add_f32_e32 v3, v17, v4
	v_add_f32_e32 v17, v18, v4
	v_add_u32_e32 v18, 0x800, v2
	ds_write2_b32 v18, v3, v17 offset0:16 offset1:148
	v_add_f32_e32 v3, v15, v4
	v_add_f32_e32 v15, v16, v4
	v_add_u32_e32 v16, 0xc00, v2
	ds_write2_b32 v16, v3, v15 offset0:24 offset1:156
	v_add_f32_e32 v3, v13, v4
	v_add_f32_e32 v13, v14, v4
	v_add_u32_e32 v14, 0x1000, v2
	ds_write2_b32 v14, v3, v13 offset0:32 offset1:164
	v_add_f32_e32 v3, v9, v4
	v_add_f32_e32 v9, v12, v4
	v_add_u32_e32 v12, 0x1400, v2
	ds_write2_b32 v12, v3, v9 offset0:40 offset1:172
	v_add_f32_e32 v3, v7, v4
	v_add_f32_e32 v7, v8, v4
	v_add_u32_e32 v8, 0x1800, v2
	ds_write2_b32 v8, v3, v7 offset0:48 offset1:180
	v_add_f32_e32 v3, v5, v4
	v_add_f32_e32 v4, v6, v4
	v_add_u32_e32 v2, 0x1c00, v2
	ds_write2_b32 v2, v3, v4 offset0:56 offset1:188
	v_ashrrev_i32_e32 v7, 2, v10
	v_lshlrev_b32_e32 v2, 1, v10
	v_and_b32_e32 v28, -8, v7
	v_and_b32_e32 v30, 62, v2
	v_mul_u32_u24_e32 v4, 0x210, v30
	v_lshlrev_b32_e32 v5, 1, v28
	s_waitcnt lgkmcnt(0)
	s_barrier
	v_add3_u32 v6, 0, v4, v5
	ds_read_b128 v[12:15], v6 offset:36864
	ds_read_b128 v[80:83], v6 offset:37392
	ds_read_b128 v[84:87], v6 offset:37120
	ds_read_b128 v[88:91], v6 offset:37648
	s_lshl_b64 s[6:7], s[60:61], 15
	s_add_u32 s8, s35, s6
	s_addc_u32 s9, s64, s7
	v_lshlrev_b32_e32 v196, 1, v30
	s_waitcnt lgkmcnt(3)
	v_lshlrev_b32_e32 v4, 16, v12
	v_and_b32_e32 v8, 0xffff0000, v12
	v_lshlrev_b32_e32 v16, 16, v13
	v_and_b32_e32 v17, 0xffff0000, v13
	v_lshlrev_b32_e32 v18, 16, v14
	v_and_b32_e32 v31, 0xffff0000, v14
	v_lshlrev_b32_e32 v32, 16, v15
	v_and_b32_e32 v33, 0xffff0000, v15
	s_nop 0
	v_ashrrev_i32_e32 v29, 31, v28
	v_lshl_add_u64 v[2:3], s[8:9], 0, v[196:197]
	v_lshlrev_b64 v[26:27], 7, v[28:29]
	s_movk_i32 s0, 0x4000
	s_waitcnt lgkmcnt(2)
	v_lshlrev_b32_e32 v5, 16, v80
	v_and_b32_e32 v9, 0xffff0000, v80
	v_lshlrev_b32_e32 v34, 16, v83
	v_and_b32_e32 v35, 0xffff0000, v83
	v_cvt_pk_bf16_f32 v15, v4, v5
	v_lshl_add_u64 v[4:5], v[2:3], 0, v[26:27]
	global_store_dword v[4:5], v15, off
	v_cvt_pk_bf16_f32 v15, v8, v9
	v_or_b32_e32 v8, 1, v28
	v_ashrrev_i32_e32 v9, 31, v8
	v_lshlrev_b64 v[24:25], 7, v[8:9]
	v_lshl_add_u64 v[8:9], v[2:3], 0, v[24:25]
	global_store_dword v[8:9], v15, off
	v_or_b32_e32 v8, 2, v28
	v_ashrrev_i32_e32 v9, 31, v8
	v_lshlrev_b32_e32 v12, 16, v81
	v_lshlrev_b64 v[22:23], 7, v[8:9]
	v_cvt_pk_bf16_f32 v12, v16, v12
	v_lshl_add_u64 v[8:9], v[2:3], 0, v[22:23]
	global_store_dword v[8:9], v12, off
	v_or_b32_e32 v8, 3, v28
	v_ashrrev_i32_e32 v9, 31, v8
	v_and_b32_e32 v13, 0xffff0000, v81
	v_lshlrev_b64 v[20:21], 7, v[8:9]
	v_cvt_pk_bf16_f32 v12, v17, v13
	v_lshl_add_u64 v[8:9], v[2:3], 0, v[20:21]
	global_store_dword v[8:9], v12, off
	v_or_b32_e32 v8, 4, v28
	v_lshlrev_b32_e32 v19, 16, v82
	v_ashrrev_i32_e32 v9, 31, v8
	v_cvt_pk_bf16_f32 v12, v18, v19
	v_lshlrev_b64 v[18:19], 7, v[8:9]
	v_lshl_add_u64 v[8:9], v[2:3], 0, v[18:19]
	global_store_dword v[8:9], v12, off
	v_or_b32_e32 v8, 5, v28
	v_ashrrev_i32_e32 v9, 31, v8
	v_and_b32_e32 v14, 0xffff0000, v82
	v_lshlrev_b64 v[16:17], 7, v[8:9]
	v_cvt_pk_bf16_f32 v12, v31, v14
	v_lshl_add_u64 v[8:9], v[2:3], 0, v[16:17]
	global_store_dword v[8:9], v12, off
	v_or_b32_e32 v8, 6, v28
	v_ashrrev_i32_e32 v9, 31, v8
	v_lshlrev_b64 v[14:15], 7, v[8:9]
	v_cvt_pk_bf16_f32 v12, v32, v34
	v_lshl_add_u64 v[8:9], v[2:3], 0, v[14:15]
	v_cvt_pk_bf16_f32 v29, v33, v35
	s_nop 0
	global_store_dword v[8:9], v12, off
	v_or_b32_e32 v8, 7, v7
	v_ashrrev_i32_e32 v9, 31, v8
	v_lshlrev_b64 v[12:13], 7, v[8:9]
	v_lshl_add_u64 v[8:9], v[2:3], 0, v[12:13]
	global_store_dword v[8:9], v29, off
	s_waitcnt lgkmcnt(1)
	v_lshlrev_b32_e32 v7, 16, v84
	v_and_b32_e32 v8, 0xffff0000, v84
	v_lshlrev_b32_e32 v9, 16, v85
	v_and_b32_e32 v29, 0xffff0000, v85
	v_lshlrev_b32_e32 v31, 16, v86
	v_and_b32_e32 v36, 0xffff0000, v86
	v_lshlrev_b32_e32 v37, 16, v87
	v_and_b32_e32 v38, 0xffff0000, v87
	s_nop 0
	v_add_co_u32_e32 v4, vcc, s0, v4
	s_movk_i32 s0, 0xff10
	s_nop 0
	v_addc_co_u32_e32 v5, vcc, 0, v5, vcc
	s_waitcnt lgkmcnt(0)
	v_lshlrev_b32_e32 v39, 16, v88
	v_cvt_pk_bf16_f32 v7, v7, v39
	global_store_dword v[4:5], v7, off
	v_add_u32_e32 v4, 0x81, v28
	v_ashrrev_i32_e32 v5, 31, v4
	v_and_b32_e32 v32, 0xffff0000, v88
	v_lshlrev_b64 v[4:5], 7, v[4:5]
	v_cvt_pk_bf16_f32 v7, v8, v32
	v_lshl_add_u64 v[4:5], v[2:3], 0, v[4:5]
	global_store_dword v[4:5], v7, off
	v_add_u32_e32 v4, 0x82, v28
	v_ashrrev_i32_e32 v5, 31, v4
	v_lshlrev_b32_e32 v40, 16, v89
	v_lshlrev_b64 v[4:5], 7, v[4:5]
	v_cvt_pk_bf16_f32 v7, v9, v40
	v_lshl_add_u64 v[4:5], v[2:3], 0, v[4:5]
	global_store_dword v[4:5], v7, off
	v_add_u32_e32 v4, 0x83, v28
	v_ashrrev_i32_e32 v5, 31, v4
	v_and_b32_e32 v33, 0xffff0000, v89
	v_lshlrev_b64 v[4:5], 7, v[4:5]
	v_cvt_pk_bf16_f32 v7, v29, v33
	v_lshl_add_u64 v[4:5], v[2:3], 0, v[4:5]
	global_store_dword v[4:5], v7, off
	v_add_u32_e32 v4, 0x84, v28
	v_ashrrev_i32_e32 v5, 31, v4
	v_lshlrev_b32_e32 v41, 16, v90
	v_lshlrev_b64 v[4:5], 7, v[4:5]
	v_cvt_pk_bf16_f32 v7, v31, v41
	v_lshl_add_u64 v[4:5], v[2:3], 0, v[4:5]
	global_store_dword v[4:5], v7, off
	v_add_u32_e32 v4, 0x85, v28
	v_ashrrev_i32_e32 v5, 31, v4
	v_and_b32_e32 v34, 0xffff0000, v90
	v_lshlrev_b64 v[4:5], 7, v[4:5]
	v_cvt_pk_bf16_f32 v7, v36, v34
	v_lshl_add_u64 v[4:5], v[2:3], 0, v[4:5]
	global_store_dword v[4:5], v7, off
	v_add_u32_e32 v4, 0x86, v28
	v_ashrrev_i32_e32 v5, 31, v4
	v_lshlrev_b32_e32 v42, 16, v91
	v_lshlrev_b64 v[4:5], 7, v[4:5]
	v_cvt_pk_bf16_f32 v7, v37, v42
	v_lshl_add_u64 v[4:5], v[2:3], 0, v[4:5]
	global_store_dword v[4:5], v7, off
	v_add_u32_e32 v4, 0x87, v28
	v_ashrrev_i32_e32 v5, 31, v4
	v_and_b32_e32 v35, 0xffff0000, v91
	v_lshlrev_b64 v[4:5], 7, v[4:5]
	v_cvt_pk_bf16_f32 v7, v38, v35
	v_lshl_add_u64 v[2:3], v[2:3], 0, v[4:5]
	v_or_b32_e32 v29, 1, v30
	v_lshl_add_u32 v46, v28, 2, s72
	global_store_dword v[2:3], v7, off
	v_mad_i32_i24 v6, v30, s0, v6
	ds_read_b128 v[2:5], v6 offset:18432
	ds_read_b128 v[80:83], v6 offset:18720
	ds_read_b128 v[84:87], v46 offset:33264
	v_mad_u32_u24 v48, v29, s1, v46
	s_nop 0
	s_nop 0
	v_mad_u32_u24 v47, v30, s1, v46
	ds_read_b128 v[34:37], v47
	s_nop 0
	s_nop 0
	ds_read_b128 v[38:41], v48
	s_lshl_b64 s[6:7], s[60:61], 14
	s_add_u32 s6, s31, s6
	s_addc_u32 s7, s34, s7
	s_waitcnt lgkmcnt(1)
	ds_read_b128 v[88:91], v46 offset:33280
	v_sub_f32_e32 v34, v84, v34
	s_waitcnt lgkmcnt(1)
	ds_read_b128 v[92:95], v47 offset:16
	v_sub_f32_e32 v30, v84, v38
	v_mul_f32_e32 v34, 0x3fb8aa3b, v34
	v_mul_f32_e32 v30, 0x3fb8aa3b, v30
	v_exp_f32_e32 v42, v34
	v_exp_f32_e32 v43, v30
	v_lshlrev_b32_e32 v45, 16, v80
	v_lshlrev_b32_e32 v44, 16, v2
	v_lshl_add_u64 v[28:29], s[6:7], 0, v[196:197]
	v_pk_mul_f32 v[42:43], v[42:43], v[44:45]
	v_lshl_add_u64 v[26:27], v[28:29], 0, v[26:27]
	v_cvt_pk_bf16_f32 v30, v42, v43
	global_store_dword v[26:27], v30, off
	v_sub_f32_e32 v26, v85, v35
	v_sub_f32_e32 v27, v85, v39
	v_mul_f32_e32 v26, 0x3fb8aa3b, v26
	v_mul_f32_e32 v27, 0x3fb8aa3b, v27
	v_exp_f32_e32 v26, v26
	v_exp_f32_e32 v27, v27
	v_and_b32_e32 v31, 0xffff0000, v80
	v_and_b32_e32 v30, 0xffff0000, v2
	v_lshl_add_u64 v[24:25], v[28:29], 0, v[24:25]
	v_pk_mul_f32 v[26:27], v[26:27], v[30:31]
	v_lshl_add_u64 v[22:23], v[28:29], 0, v[22:23]
	v_cvt_pk_bf16_f32 v2, v26, v27
	global_store_dword v[24:25], v2, off
	v_sub_f32_e32 v2, v86, v36
	v_mul_f32_e32 v2, 0x3fb8aa3b, v2
	v_exp_f32_e32 v24, v2
	v_sub_f32_e32 v2, v86, v40
	v_mul_f32_e32 v2, 0x3fb8aa3b, v2
	v_exp_f32_e32 v25, v2
	v_lshlrev_b32_e32 v27, 16, v81
	v_lshlrev_b32_e32 v26, 16, v3
	v_and_b32_e32 v7, 0xffff0000, v81
	v_pk_mul_f32 v[24:25], v[24:25], v[26:27]
	v_and_b32_e32 v6, 0xffff0000, v3
	v_cvt_pk_bf16_f32 v2, v24, v25
	global_store_dword v[22:23], v2, off
	v_sub_f32_e32 v2, v87, v37
	v_mul_f32_e32 v2, 0x3fb8aa3b, v2
	v_exp_f32_e32 v22, v2
	v_sub_f32_e32 v2, v87, v41
	ds_read_b128 v[30:33], v48 offset:16
	v_mul_f32_e32 v2, 0x3fb8aa3b, v2
	v_exp_f32_e32 v23, v2
	s_movk_i32 s0, 0x80
	v_cmp_gt_i32_e32 vcc, s0, v10
	v_pk_mul_f32 v[2:3], v[22:23], v[6:7]
	s_nop 0
	v_cvt_pk_bf16_f32 v6, v2, v3
	v_lshl_add_u64 v[2:3], v[28:29], 0, v[20:21]
	global_store_dword v[2:3], v6, off
	s_nop 0
	s_nop 0
	s_nop 0
	v_lshlrev_b32_e32 v7, 16, v82
	v_lshlrev_b32_e32 v6, 16, v4
	s_waitcnt lgkmcnt(1)
	v_sub_f32_e32 v2, v88, v92
	s_waitcnt lgkmcnt(0)
	v_sub_f32_e32 v3, v88, v30
	v_mul_f32_e32 v2, 0x3fb8aa3b, v2
	v_mul_f32_e32 v3, 0x3fb8aa3b, v3
	v_exp_f32_e32 v2, v2
	v_exp_f32_e32 v3, v3
	s_nop 0
	v_pk_mul_f32 v[2:3], v[2:3], v[6:7]
	s_nop 0
	v_cvt_pk_bf16_f32 v6, v2, v3
	v_lshl_add_u64 v[2:3], v[28:29], 0, v[18:19]
	global_store_dword v[2:3], v6, off
	v_sub_f32_e32 v2, v89, v93
	v_sub_f32_e32 v3, v89, v31
	v_mul_f32_e32 v2, 0x3fb8aa3b, v2
	v_mul_f32_e32 v3, 0x3fb8aa3b, v3
	v_exp_f32_e32 v2, v2
	v_exp_f32_e32 v3, v3
	v_and_b32_e32 v7, 0xffff0000, v82
	v_and_b32_e32 v6, 0xffff0000, v4
	v_pk_mul_f32 v[2:3], v[2:3], v[6:7]
	s_nop 0
	v_cvt_pk_bf16_f32 v4, v2, v3
	v_lshl_add_u64 v[2:3], v[28:29], 0, v[16:17]
	global_store_dword v[2:3], v4, off
	v_sub_f32_e32 v2, v90, v94
	v_sub_f32_e32 v3, v90, v32
	v_mul_f32_e32 v2, 0x3fb8aa3b, v2
	v_mul_f32_e32 v3, 0x3fb8aa3b, v3
	v_exp_f32_e32 v2, v2
	v_exp_f32_e32 v3, v3
	v_lshlrev_b32_e32 v7, 16, v83
	v_lshlrev_b32_e32 v6, 16, v5
	v_pk_mul_f32 v[2:3], v[2:3], v[6:7]
	s_nop 0
	v_cvt_pk_bf16_f32 v4, v2, v3
	v_lshl_add_u64 v[2:3], v[28:29], 0, v[14:15]
	global_store_dword v[2:3], v4, off
	v_sub_f32_e32 v2, v91, v95
	v_sub_f32_e32 v3, v91, v33
	v_mul_f32_e32 v2, 0x3fb8aa3b, v2
	v_mul_f32_e32 v3, 0x3fb8aa3b, v3
	v_exp_f32_e32 v2, v2
	v_exp_f32_e32 v3, v3
	v_and_b32_e32 v7, 0xffff0000, v83
	v_and_b32_e32 v6, 0xffff0000, v5
	v_pk_mul_f32 v[2:3], v[2:3], v[6:7]
	s_nop 0
	v_cvt_pk_bf16_f32 v4, v2, v3
	v_lshl_add_u64 v[2:3], v[28:29], 0, v[12:13]
	global_store_dword v[2:3], v4, off
	s_and_saveexec_b64 s[6:7], vcc
	s_cbranch_execz .LBB0_1478
	v_lshl_add_u32 v2, v10, 2, s72
	ds_read_b32 v2, v2 offset:33264
	s_lshl_b64 s[8:9], s[60:61], 9
	s_add_u32 s8, s67, s8
	s_addc_u32 s9, s68, s9
	s_waitcnt lgkmcnt(0)
	v_mul_f32_e32 v2, 0x3fb8aa3b, v2
	v_exp_f32_e32 v4, v2
	v_lshl_add_u64 v[2:3], v[10:11], 2, s[8:9]
	global_store_dword v[2:3], v4, off

.LBB0_1480:
	v_ashrrev_i32_e32 v11, 4, v3
	v_and_b32_e32 v8, 0x78, v2
	v_mul_lo_u32 v4, v11, s60
	v_lshlrev_b32_e32 v196, 1, v8
	v_mul_lo_u32 v9, v11, s1
	v_lshlrev_b32_e32 v8, 2, v8
	v_add3_u32 v28, 0, v4, v196
	ds_read_b128 v[4:7], v28
	ds_read_b128 v[12:15], v28 offset:18432
	v_add3_u32 v8, s72, v9, v8
	ds_read_b128 v[16:19], v8
	ds_read_b128 v[20:23], v8 offset:16
	s_nop 0
	s_nop 0
	s_nop 0
	s_nop 0
	v_cmp_lt_i32_e32 vcc, s84, v3
	v_add_u32_e32 v2, 0x1000, v2
	s_waitcnt lgkmcnt(3)
	v_lshlrev_b32_e32 v24, 16, v4
	s_waitcnt lgkmcnt(1)
	v_mul_f32_e32 v9, 0xbfb8aa3b, v16
	v_mul_f32_e32 v8, 0x3fb8aa3b, v16
	v_exp_f32_e32 v16, v9
	v_mul_f32_e32 v9, 0x3fb8aa3b, v17
	v_exp_f32_e32 v8, v8
	v_exp_f32_e32 v9, v9
	v_and_b32_e32 v25, 0xffff0000, v4
	v_mul_f32_e32 v4, 0xbfb8aa3b, v17
	v_exp_f32_e32 v17, v4
	v_pk_mul_f32 v[8:9], v[8:9], s[0:1] op_sel_hi:[1,0]
	v_mul_f32_e32 v4, 0x3fb8aa3b, v18
	v_pk_mul_f32 v[8:9], v[8:9], v[24:25]
	v_lshlrev_b32_e32 v24, 16, v12
	v_and_b32_e32 v25, 0xffff0000, v12
	v_pk_mul_f32 v[16:17], v[16:17], v[24:25]
	v_exp_f32_e32 v24, v4
	v_mul_f32_e32 v4, 0xbfb8aa3b, v18
	v_lshlrev_b32_e32 v26, 16, v5
	v_and_b32_e32 v27, 0xffff0000, v5
	v_mul_f32_e32 v5, 0xbfb8aa3b, v19
	v_exp_f32_e32 v4, v4
	v_exp_f32_e32 v5, v5
	v_mul_f32_e32 v12, 0x3fb8aa3b, v19
	v_exp_f32_e32 v25, v12
	v_lshlrev_b32_e32 v12, 16, v13
	v_and_b32_e32 v13, 0xffff0000, v13
	v_pk_mul_f32 v[12:13], v[4:5], v[12:13]
	s_waitcnt lgkmcnt(0)
	v_mul_f32_e32 v5, 0xbfb8aa3b, v20
	v_mul_f32_e32 v4, 0x3fb8aa3b, v20
	v_exp_f32_e32 v18, v5
	v_mul_f32_e32 v5, 0x3fb8aa3b, v21
	v_exp_f32_e32 v4, v4
	v_exp_f32_e32 v5, v5
	v_pk_mul_f32 v[24:25], v[24:25], s[0:1] op_sel_hi:[1,0]
	v_lshlrev_b32_e32 v20, 16, v7
	v_pk_mul_f32 v[24:25], v[24:25], v[26:27]
	v_lshlrev_b32_e32 v26, 16, v6
	v_and_b32_e32 v27, 0xffff0000, v6
	v_pk_mul_f32 v[4:5], v[4:5], s[0:1] op_sel_hi:[1,0]
	s_or_b64 s[62:63], vcc, s[62:63]
	v_pk_mul_f32 v[26:27], v[4:5], v[26:27]
	v_mul_f32_e32 v4, 0xbfb8aa3b, v21
	v_exp_f32_e32 v19, v4
	v_lshlrev_b32_e32 v4, 16, v14
	v_and_b32_e32 v5, 0xffff0000, v14
	v_and_b32_e32 v21, 0xffff0000, v7
	v_pk_mul_f32 v[18:19], v[18:19], v[4:5]
	v_mul_f32_e32 v5, 0xbfb8aa3b, v22
	v_mul_f32_e32 v4, 0x3fb8aa3b, v22
	v_exp_f32_e32 v6, v5
	v_mul_f32_e32 v5, 0x3fb8aa3b, v23
	v_exp_f32_e32 v4, v4
	v_exp_f32_e32 v5, v5
	s_nop 0
	v_pk_mul_f32 v[4:5], v[4:5], s[0:1] op_sel_hi:[1,0]
	s_nop 0
	v_pk_mul_f32 v[20:21], v[4:5], v[20:21]
	v_mul_f32_e32 v4, 0xbfb8aa3b, v23
	v_exp_f32_e32 v7, v4
	v_lshlrev_b32_e32 v4, 16, v15
	v_and_b32_e32 v5, 0xffff0000, v15
	v_pk_mul_f32 v[14:15], v[6:7], v[4:5]
	v_cvt_pk_bf16_f32 v4, v8, v9
	v_lshlrev_b32_e32 v8, 7, v11
	v_ashrrev_i32_e32 v9, 31, v8
	v_lshl_add_u64 v[8:9], v[8:9], 1, s[58:59]
	v_cvt_pk_bf16_f32 v5, v24, v25
	v_cvt_pk_bf16_f32 v6, v26, v27
	v_cvt_pk_bf16_f32 v7, v20, v21
	v_lshl_add_u64 v[8:9], v[8:9], 0, v[196:197]
	ds_write_b128 v28, v[4:7]
	global_store_dwordx4 v[8:9], v[4:7], off
	s_nop 1
	v_cvt_pk_bf16_f32 v4, v16, v17
	v_cvt_pk_bf16_f32 v5, v12, v13
	v_cvt_pk_bf16_f32 v6, v18, v19
	v_cvt_pk_bf16_f32 v7, v14, v15
	ds_write_b128 v28, v[4:7] offset:18432
	v_add_u32_e32 v4, 0x200, v3
	v_mov_b32_e32 v3, v4
	s_andn2_b64 exec, exec, s[62:63]
	s_cbranch_execnz .LBB0_1480
.LBB0_1481:
	s_movk_i32 s1, 0x120
	s_or_b64 exec, exec, s[52:53]
	s_ashr_i32 s8, s70, 7
	v_and_b32_e32 v2, 15, v10
	s_waitcnt lgkmcnt(0)
	s_barrier
	s_lshr_b32 s0, s70, 5
	s_lshl_b32 s52, s8, 4
	v_and_b32_e32 v4, 48, v10
	s_and_b32 s9, s0, 2
	v_or_b32_e32 v3, s52, v2
	v_add_u32_e32 v12, 0, v4
	v_mad_u64_u32 v[8:9], s[58:59], v3, s1, v[12:13]
	s_cmp_le_i32 s9, s8
	v_lshl_or_b32 v196, s9, 4, v2
	v_mov_b32_e32 v2, 0
	v_mov_b32_e32 v4, 0
	v_mov_b32_e32 v5, 0
	v_mov_b32_e32 v6, 0
	v_mov_b32_e32 v7, 0
	s_cbranch_scc0 .LBB0_1483
	ds_read_b128 v[4:7], v8
	v_mad_u32_u24 v3, v196, s1, v12
	ds_read_b128 v[14:17], v3 offset:18432
	ds_read_b128 v[80:83], v8 offset:64
	ds_read_b128 v[18:21], v3 offset:18496
	s_nop 0
	s_nop 0
	s_waitcnt lgkmcnt(2)
	ds_read_b128 v[84:87], v8 offset:128
	ds_read_b128 v[88:91], v3 offset:18560
	v_mfma_f32_16x16x32_bf16 v[4:7], v[4:7], v[14:17], 0
	s_nop 0
	s_nop 0
	s_waitcnt lgkmcnt(2)
	ds_read_b128 v[92:95], v8 offset:192
	ds_read_b128 v[96:99], v3 offset:18624
	v_mfma_f32_16x16x32_bf16 v[4:7], v[80:83], v[18:21], v[4:7]
	s_nop 0
	s_nop 0
	s_waitcnt lgkmcnt(2)
	v_mfma_f32_16x16x32_bf16 v[4:7], v[84:87], v[88:91], v[4:7]
	s_nop 0
	s_nop 0
	s_waitcnt lgkmcnt(0)
	v_mfma_f32_16x16x32_bf16 v[4:7], v[92:95], v[96:99], v[4:7]
.LBB0_1483:
	v_lshrrev_b32_e32 v3, 2, v10
	v_and_or_b32 v9, v3, 12, s52
	v_lshlrev_b32_e32 v10, 6, v9
	s_add_u32 s6, s29, s6
	v_or_b32_e32 v14, v10, v196
	s_addc_u32 s7, s30, s7
	s_nop 1
	v_cvt_pk_bf16_f32 v3, v4, s0
	v_cmp_le_i32_e32 vcc, v196, v9
	v_ashrrev_i32_e32 v15, 31, v14
	v_lshl_add_u64 v[14:15], v[14:15], 1, s[6:7]
	v_cndmask_b32_e32 v3, 0, v3, vcc
	v_or_b32_e32 v13, 1, v9
	global_store_short v[14:15], v3, off
	v_lshlrev_b32_e32 v14, 6, v13
	v_or_b32_e32 v4, v14, v196
	v_cvt_pk_bf16_f32 v3, v5, s0
	v_cmp_le_i32_e32 vcc, v196, v13
	v_ashrrev_i32_e32 v5, 31, v4
	v_lshl_add_u64 v[4:5], v[4:5], 1, s[6:7]
	v_cndmask_b32_e32 v3, 0, v3, vcc
	v_or_b32_e32 v17, 2, v9
	global_store_short v[4:5], v3, off
	v_cvt_pk_bf16_f32 v3, v6, s0
	v_lshlrev_b32_e32 v6, 6, v17
	v_or_b32_e32 v4, v6, v196
	v_cmp_le_i32_e32 vcc, v196, v17
	v_ashrrev_i32_e32 v5, 31, v4
	v_or_b32_e32 v18, 3, v9
	v_cndmask_b32_e32 v3, 0, v3, vcc
	v_lshl_add_u64 v[4:5], v[4:5], 1, s[6:7]
	v_lshlrev_b32_e32 v16, 6, v18
	global_store_short v[4:5], v3, off
	v_or_b32_e32 v4, v16, v196
	v_cvt_pk_bf16_f32 v3, v7, s0
	v_cmp_le_i32_e32 vcc, v196, v18
	v_ashrrev_i32_e32 v5, 31, v4
	v_lshl_add_u64 v[4:5], v[4:5], 1, s[6:7]
	v_cndmask_b32_e32 v3, 0, v3, vcc
	global_store_short v[4:5], v3, off
	s_cmp_ge_i32 s9, s8
	v_or_b32_e32 v19, 16, v196
	v_mov_b32_e32 v3, 0
	v_mov_b32_e32 v4, 0
	v_mov_b32_e32 v5, 0
	s_cbranch_scc1 .LBB0_1455
	ds_read_b128 v[2:5], v8
	v_mad_u32_u24 v7, v19, s1, v12
	ds_read_b128 v[20:23], v7 offset:18432
	ds_read_b128 v[80:83], v8 offset:64
	ds_read_b128 v[24:27], v7 offset:18496
	s_nop 0
	s_nop 0
	s_waitcnt lgkmcnt(2)
	ds_read_b128 v[84:87], v8 offset:128
	ds_read_b128 v[88:91], v7 offset:18560
	v_mfma_f32_16x16x32_bf16 v[2:5], v[2:5], v[20:23], 0
	s_nop 0
	s_nop 0
	s_waitcnt lgkmcnt(2)
	v_mfma_f32_16x16x32_bf16 v[2:5], v[80:83], v[24:27], v[2:5]
	s_nop 0
	s_nop 0
	s_waitcnt lgkmcnt(0)
	v_mfma_f32_16x16x32_bf16 v[2:5], v[84:87], v[88:91], v[2:5]
	ds_read_b128 v[20:23], v8 offset:192
	ds_read_b128 v[24:27], v7 offset:18624
	s_waitcnt lgkmcnt(0)
	v_mfma_f32_16x16x32_bf16 v[2:5], v[20:23], v[24:27], v[2:5]
	s_branch .LBB0_1455
